# SSM carry-GEMM epilogue (P3): y/u row loads software-pipelined four loads ahead (32-bit offsets from the workspace base, address pre-pass) instead of a load-wait round trip per step
# speedup vs baseline: 1.0056x; 1.0017x over previous
.LBB0_411:
	v_mov_b32_e32 v138, v1
	v_mov_b32_e32 v139, v152
	s_lshl_b32 s1, s1, 8
	s_add_i32 s1, s1, s90
	s_lshl_b32 s0, s0, 8
	v_lshlrev_b32_e32 v139, 3, v139
	v_add_u32_e32 v142, s1, v138
	s_or_b32 s0, s0, s91
	s_ashr_i32 s45, s44, 31
	v_ashrrev_i32_e32 v143, 31, v142
	v_add_u32_e32 v155, s0, v139
	s_lshl_b64 s[60:61], s[44:45], 14
	v_lshlrev_b64 v[144:145], 5, v[142:143]
	v_ashrrev_i32_e32 v140, 4, v155
	v_lshl_add_u64 v[146:147], v[144:145], 0, s[60:61]
	v_ashrrev_i32_e32 v141, 31, v140
	v_and_b32_e32 v168, 8, v139
	v_lshl_add_u64 v[138:139], v[146:147], 0, v[140:141]
	v_lshlrev_b64 v[156:157], 5, v[138:139]
	v_lshlrev_b32_e32 v138, 1, v168
	v_or_b32_e32 v156, v156, v138
	v_lshl_add_u64 v[148:149], s[12:13], 0, v[156:157]
	global_load_dwordx4 v[148:151], v[148:149], off
	s_lshl_b32 s46, s44, 4
	s_ashr_i32 s47, s46, 31
	s_lshl_b64 s[0:1], s[46:47], 2
	s_add_u32 s44, s74, s0
	s_addc_u32 s45, s75, s1
	v_lshlrev_b32_e32 v143, 2, v168
	s_waitcnt vmcnt(0)
	v_lshl_add_u64 v[244:245], s[14:15], 0, v[156:157]
	v_subrev_u32_e32 v169, s78, v244
	v_add_u32_e32 v244, 0x80, v155
	v_ashrrev_i32_e32 v244, 4, v244
	v_ashrrev_i32_e32 v245, 31, v244
	v_lshl_add_u64 v[246:247], v[146:147], 0, v[244:245]
	v_lshlrev_b64 v[246:247], 5, v[246:247]
	v_or_b32_e32 v246, v246, v138
	v_lshl_add_u64 v[248:249], s[12:13], 0, v[246:247]
	v_subrev_u32_e32 v202, s78, v248
	v_lshl_add_u64 v[246:247], s[14:15], 0, v[246:247]
	v_subrev_u32_e32 v203, s78, v246
	v_add_u32_e32 v246, 16, v142
	v_ashrrev_i32_e32 v247, 31, v246
	v_lshlrev_b64 v[246:247], 5, v[246:247]
	v_lshl_add_u64 v[246:247], v[246:247], 0, s[60:61]
	v_lshl_add_u64 v[248:249], v[246:247], 0, v[140:141]
	v_lshlrev_b64 v[248:249], 5, v[248:249]
	v_or_b32_e32 v248, v248, v138
	v_lshl_add_u64 v[250:251], s[12:13], 0, v[248:249]
	v_subrev_u32_e32 v204, s78, v250
	v_lshl_add_u64 v[248:249], s[14:15], 0, v[248:249]
	v_subrev_u32_e32 v205, s78, v248
	v_lshl_add_u64 v[246:247], v[246:247], 0, v[244:245]
	v_lshlrev_b64 v[246:247], 5, v[246:247]
	v_or_b32_e32 v246, v246, v138
	v_lshl_add_u64 v[248:249], s[12:13], 0, v[246:247]
	v_subrev_u32_e32 v206, s78, v248
	v_lshl_add_u64 v[246:247], s[14:15], 0, v[246:247]
	v_subrev_u32_e32 v207, s78, v246
	v_add_u32_e32 v246, 32, v142
	v_ashrrev_i32_e32 v247, 31, v246
	v_lshlrev_b64 v[246:247], 5, v[246:247]
	v_lshl_add_u64 v[246:247], v[246:247], 0, s[60:61]
	v_lshl_add_u64 v[248:249], v[246:247], 0, v[140:141]
	v_lshlrev_b64 v[248:249], 5, v[248:249]
	v_or_b32_e32 v248, v248, v138
	v_lshl_add_u64 v[250:251], s[12:13], 0, v[248:249]
	v_subrev_u32_e32 v208, s78, v250
	v_lshl_add_u64 v[248:249], s[14:15], 0, v[248:249]
	v_subrev_u32_e32 v209, s78, v248
	v_lshl_add_u64 v[246:247], v[246:247], 0, v[244:245]
	v_lshlrev_b64 v[246:247], 5, v[246:247]
	v_or_b32_e32 v246, v246, v138
	v_lshl_add_u64 v[248:249], s[12:13], 0, v[246:247]
	v_subrev_u32_e32 v210, s78, v248
	v_lshl_add_u64 v[246:247], s[14:15], 0, v[246:247]
	v_subrev_u32_e32 v211, s78, v246
	v_add_u32_e32 v246, 48, v142
	v_ashrrev_i32_e32 v247, 31, v246
	v_lshlrev_b64 v[246:247], 5, v[246:247]
	v_lshl_add_u64 v[246:247], v[246:247], 0, s[60:61]
	v_lshl_add_u64 v[248:249], v[246:247], 0, v[140:141]
	v_lshlrev_b64 v[248:249], 5, v[248:249]
	v_or_b32_e32 v248, v248, v138
	v_lshl_add_u64 v[250:251], s[12:13], 0, v[248:249]
	v_subrev_u32_e32 v212, s78, v250
	v_lshl_add_u64 v[248:249], s[14:15], 0, v[248:249]
	v_subrev_u32_e32 v213, s78, v248
	v_lshl_add_u64 v[246:247], v[246:247], 0, v[244:245]
	v_lshlrev_b64 v[246:247], 5, v[246:247]
	v_or_b32_e32 v246, v246, v138
	v_lshl_add_u64 v[248:249], s[12:13], 0, v[246:247]
	v_subrev_u32_e32 v214, s78, v248
	v_lshl_add_u64 v[246:247], s[14:15], 0, v[246:247]
	v_subrev_u32_e32 v215, s78, v246
	v_add_u32_e32 v246, 0x80, v142
	v_ashrrev_i32_e32 v247, 31, v246
	v_lshlrev_b64 v[246:247], 5, v[246:247]
	v_lshl_add_u64 v[246:247], v[246:247], 0, s[60:61]
	v_lshl_add_u64 v[248:249], v[246:247], 0, v[140:141]
	v_lshlrev_b64 v[248:249], 5, v[248:249]
	v_or_b32_e32 v248, v248, v138
	v_lshl_add_u64 v[250:251], s[12:13], 0, v[248:249]
	v_subrev_u32_e32 v216, s78, v250
	v_lshl_add_u64 v[248:249], s[14:15], 0, v[248:249]
	v_subrev_u32_e32 v217, s78, v248
	v_lshl_add_u64 v[246:247], v[246:247], 0, v[244:245]
	v_lshlrev_b64 v[246:247], 5, v[246:247]
	v_or_b32_e32 v246, v246, v138
	v_lshl_add_u64 v[248:249], s[12:13], 0, v[246:247]
	v_subrev_u32_e32 v218, s78, v248
	v_lshl_add_u64 v[246:247], s[14:15], 0, v[246:247]
	v_subrev_u32_e32 v219, s78, v246
	v_add_u32_e32 v246, 0x90, v142
	v_ashrrev_i32_e32 v247, 31, v246
	v_lshlrev_b64 v[246:247], 5, v[246:247]
	v_lshl_add_u64 v[246:247], v[246:247], 0, s[60:61]
	v_lshl_add_u64 v[248:249], v[246:247], 0, v[140:141]
	v_lshlrev_b64 v[248:249], 5, v[248:249]
	v_or_b32_e32 v248, v248, v138
	v_lshl_add_u64 v[250:251], s[12:13], 0, v[248:249]
	v_subrev_u32_e32 v220, s78, v250
	v_lshl_add_u64 v[248:249], s[14:15], 0, v[248:249]
	v_subrev_u32_e32 v221, s78, v248
	v_lshl_add_u64 v[246:247], v[246:247], 0, v[244:245]
	v_lshlrev_b64 v[246:247], 5, v[246:247]
	v_or_b32_e32 v246, v246, v138
	v_lshl_add_u64 v[248:249], s[12:13], 0, v[246:247]
	v_subrev_u32_e32 v222, s78, v248
	v_lshl_add_u64 v[246:247], s[14:15], 0, v[246:247]
	v_subrev_u32_e32 v223, s78, v246
	v_add_u32_e32 v246, 0xa0, v142
	v_ashrrev_i32_e32 v247, 31, v246
	v_lshlrev_b64 v[246:247], 5, v[246:247]
	v_lshl_add_u64 v[246:247], v[246:247], 0, s[60:61]
	v_lshl_add_u64 v[248:249], v[246:247], 0, v[140:141]
	v_lshlrev_b64 v[248:249], 5, v[248:249]
	v_or_b32_e32 v248, v248, v138
	v_lshl_add_u64 v[250:251], s[12:13], 0, v[248:249]
	v_subrev_u32_e32 v224, s78, v250
	v_lshl_add_u64 v[248:249], s[14:15], 0, v[248:249]
	v_subrev_u32_e32 v226, s78, v248
	v_lshl_add_u64 v[246:247], v[246:247], 0, v[244:245]
	v_lshlrev_b64 v[246:247], 5, v[246:247]
	v_or_b32_e32 v246, v246, v138
	v_lshl_add_u64 v[248:249], s[12:13], 0, v[246:247]
	v_subrev_u32_e32 v227, s78, v248
	v_lshl_add_u64 v[246:247], s[14:15], 0, v[246:247]
	v_subrev_u32_e32 v228, s78, v246
	v_add_u32_e32 v246, 0xb0, v142
	v_ashrrev_i32_e32 v247, 31, v246
	v_lshlrev_b64 v[246:247], 5, v[246:247]
	v_lshl_add_u64 v[246:247], v[246:247], 0, s[60:61]
	v_lshl_add_u64 v[248:249], v[246:247], 0, v[140:141]
	v_lshlrev_b64 v[248:249], 5, v[248:249]
	v_or_b32_e32 v248, v248, v138
	v_lshl_add_u64 v[250:251], s[12:13], 0, v[248:249]
	v_subrev_u32_e32 v232, s78, v250
	v_lshl_add_u64 v[248:249], s[14:15], 0, v[248:249]
	v_subrev_u32_e32 v233, s78, v248
	v_lshl_add_u64 v[244:245], v[246:247], 0, v[244:245]
	v_lshlrev_b64 v[244:245], 5, v[244:245]
	v_or_b32_e32 v244, v244, v138
	v_lshl_add_u64 v[246:247], s[12:13], 0, v[244:245]
	v_subrev_u32_e32 v240, s78, v246
	v_lshl_add_u64 v[244:245], s[14:15], 0, v[244:245]
	v_subrev_u32_e32 v241, s78, v244
	s_lshl_b64 s[46:47], s[46:47], 1
	s_and_b64 vcc, exec, s[4:5]
	v_lshlrev_b32_e32 v158, 16, v148
	v_and_b32_e32 v159, 0xffff0000, v148
	v_lshlrev_b32_e32 v148, 16, v149
	v_and_b32_e32 v149, 0xffff0000, v149
	v_pk_add_f32 v[158:159], v[122:123], v[158:159]
	v_lshl_add_u64 v[122:123], s[14:15], 0, v[156:157]
	v_pk_add_f32 v[148:149], v[124:125], v[148:149]
	global_load_dwordx4 v[170:173], v169, s[78:79]
	global_load_dwordx4 v[174:177], v143, s[44:45] offset:16
	global_load_dwordx4 v[178:181], v143, s[44:45]
	global_load_dwordx4 v[182:185], v202, s[78:79]
	global_load_dwordx4 v[186:189], v203, s[78:79]
	s_waitcnt vmcnt(4)
	v_lshlrev_b32_e32 v160, 16, v150
	v_and_b32_e32 v161, 0xffff0000, v150
	v_lshlrev_b32_e32 v150, 16, v151
	v_and_b32_e32 v151, 0xffff0000, v151
	v_pk_add_f32 v[160:161], v[126:127], v[160:161]
	v_pk_add_f32 v[150:151], v[128:129], v[150:151]
	v_lshlrev_b32_e32 v156, 16, v170
	v_and_b32_e32 v157, 0xffff0000, v170
	v_lshlrev_b32_e32 v162, 16, v171
	v_and_b32_e32 v163, 0xffff0000, v171
	v_lshlrev_b32_e32 v164, 16, v172
	v_and_b32_e32 v165, 0xffff0000, v172
	v_lshlrev_b32_e32 v166, 16, v173
	v_and_b32_e32 v167, 0xffff0000, v173
	global_load_dwordx4 v[190:193], v143, s[44:45] offset:16
	s_waitcnt vmcnt(4)
	global_load_dwordx4 v[194:197], v143, s[44:45]
	s_waitcnt vmcnt(4)
	v_pk_fma_f32 v[124:125], v[180:181], v[162:163], v[148:149]
	v_pk_fma_f32 v[148:149], v[178:179], v[156:157], v[158:159]
	v_pk_fma_f32 v[122:123], v[176:177], v[166:167], v[150:151]
	v_pk_fma_f32 v[128:129], v[174:175], v[164:165], v[160:161]
	v_mul_f32_e32 v126, 0x3d372713, v148
	v_mul_f32_e32 v127, 0x3d372713, v128
	v_mul_f32_e32 v127, v128, v127
	v_fma_f32 v127, v128, v127, v128
	v_mul_f32_e32 v127, 0x3f4c422a, v127
	v_mul_f32_e32 v127, 0x4038aa3b, v127
	v_exp_f32_e32 v127, v127
	v_mul_f32_e32 v139, 0x3d372713, v129
	v_mul_f32_e32 v139, v129, v139
	v_fma_f32 v139, v129, v139, v129
	v_add_f32_e32 v127, 1.0, v127
	v_mul_f32_e32 v139, 0x3f4c422a, v139
	v_rcp_f32_e32 v150, v127
	v_mul_f32_e32 v127, 0x3d372713, v149
	v_mul_f32_e32 v139, 0x4038aa3b, v139
	v_mul_f32_e32 v126, v148, v126
	v_mul_f32_e32 v127, v149, v127
	v_exp_f32_e32 v139, v139
	v_fma_f32 v126, v148, v126, v148
	v_fma_f32 v127, v149, v127, v149
	v_mul_f32_e32 v126, 0x3f4c422a, v126
	v_mul_f32_e32 v127, 0x3f4c422a, v127
	v_mul_f32_e32 v126, 0x4038aa3b, v126
	v_mul_f32_e32 v127, 0x4038aa3b, v127
	v_exp_f32_e32 v126, v126
	v_exp_f32_e32 v127, v127
	v_add_f32_e32 v139, 1.0, v139
	v_rcp_f32_e32 v151, v139
	v_mul_f32_e32 v139, 0x3d372713, v124
	v_mul_f32_e32 v139, v124, v139
	v_fma_f32 v139, v124, v139, v124
	v_add_f32_e32 v126, 1.0, v126
	v_add_f32_e32 v127, 1.0, v127
	v_mul_f32_e32 v139, 0x3f4c422a, v139
	v_rcp_f32_e32 v126, v126
	v_rcp_f32_e32 v127, v127
	v_mul_f32_e32 v139, 0x4038aa3b, v139
	v_exp_f32_e32 v139, v139
	v_pk_mul_f32 v[148:149], v[148:149], 0.5 op_sel_hi:[1,0]
	v_pk_fma_f32 v[126:127], v[126:127], 2.0, 1.0 op_sel_hi:[1,0,0] neg_lo:[1,0,0] neg_hi:[1,0,0]
	v_pk_mul_f32 v[128:129], v[128:129], 0.5 op_sel_hi:[1,0]
	v_pk_add_f32 v[126:127], v[126:127], 1.0 op_sel_hi:[1,0]
	v_add_f32_e32 v139, 1.0, v139
	v_pk_mul_f32 v[126:127], v[148:149], v[126:127]
	v_pk_fma_f32 v[148:149], v[150:151], 2.0, 1.0 op_sel_hi:[1,0,0] neg_lo:[1,0,0] neg_hi:[1,0,0]
	v_rcp_f32_e32 v150, v139
	v_mul_f32_e32 v139, 0x3d372713, v122
	v_mul_f32_e32 v139, v122, v139
	v_fma_f32 v139, v122, v139, v122
	v_mul_f32_e32 v139, 0x3f4c422a, v139
	v_mul_f32_e32 v139, 0x4038aa3b, v139
	v_exp_f32_e32 v139, v139
	v_pk_add_f32 v[148:149], v[148:149], 1.0 op_sel_hi:[1,0]
	v_add_f32_e32 v139, 1.0, v139
	v_pk_mul_f32 v[128:129], v[128:129], v[148:149]
	v_rcp_f32_e32 v148, v139
	v_mul_f32_e32 v139, 0x3d372713, v125
	v_mul_f32_e32 v139, v125, v139
	v_fma_f32 v139, v125, v139, v125
	v_mul_f32_e32 v139, 0x3f4c422a, v139
	v_mul_f32_e32 v139, 0x4038aa3b, v139
	v_exp_f32_e32 v139, v139
	v_pk_mul_f32 v[124:125], v[124:125], 0.5 op_sel_hi:[1,0]
	v_add_f32_e32 v139, 1.0, v139
	v_rcp_f32_e32 v151, v139
	v_mul_f32_e32 v139, 0x3d372713, v123
	v_mul_f32_e32 v139, v123, v139
	v_fma_f32 v139, v123, v139, v123
	v_mul_f32_e32 v139, 0x3f4c422a, v139
	v_mul_f32_e32 v139, 0x4038aa3b, v139
	v_exp_f32_e32 v139, v139
	v_pk_fma_f32 v[150:151], v[150:151], 2.0, 1.0 op_sel_hi:[1,0,0] neg_lo:[1,0,0] neg_hi:[1,0,0]
	v_pk_mul_f32 v[122:123], v[122:123], 0.5 op_sel_hi:[1,0]
	v_pk_add_f32 v[150:151], v[150:151], 1.0 op_sel_hi:[1,0]
	v_add_f32_e32 v139, 1.0, v139
	v_rcp_f32_e32 v149, v139
	v_pk_mul_f32 v[124:125], v[124:125], v[150:151]
	v_lshl_add_u64 v[150:151], v[144:145], 0, v[140:141]
	v_mov_b32_e32 v139, v0
	v_pk_fma_f32 v[148:149], v[148:149], 2.0, 1.0 op_sel_hi:[1,0,0] neg_lo:[1,0,0] neg_hi:[1,0,0]
	s_nop 0
	v_pk_add_f32 v[148:149], v[148:149], 1.0 op_sel_hi:[1,0]
	s_nop 0
	v_pk_mul_f32 v[148:149], v[122:123], v[148:149]
	v_cvt_pk_bf16_f32 v122, v126, v127
	v_lshlrev_b64 v[126:127], 10, v[150:151]
	v_lshl_add_u64 v[126:127], s[16:17], 0, v[126:127]
	v_lshl_add_u64 v[126:127], v[126:127], 0, s[46:47]
	v_cvt_pk_bf16_f32 v123, v124, v125
	v_cvt_pk_bf16_f32 v124, v128, v129
	v_cvt_pk_bf16_f32 v125, v148, v149
	v_lshl_add_u64 v[126:127], v[126:127], 0, v[138:139]
	global_store_dwordx4 v[126:127], v[122:125], off
	s_nop 1
	v_add_u32_e32 v122, 0x80, v155
	v_ashrrev_i32_e32 v122, 4, v122
	v_ashrrev_i32_e32 v123, 31, v122
	v_lshl_add_u64 v[124:125], v[146:147], 0, v[122:123]
	v_lshlrev_b64 v[128:129], 5, v[124:125]
	v_or_b32_e32 v128, v128, v138
	v_lshl_add_u64 v[124:125], s[12:13], 0, v[128:129]
	global_load_dwordx4 v[198:201], v143, s[44:45] offset:16
	s_waitcnt vmcnt(5)
	v_lshlrev_b32_e32 v146, 16, v182
	v_and_b32_e32 v147, 0xffff0000, v182
	v_lshlrev_b32_e32 v124, 16, v183
	v_and_b32_e32 v125, 0xffff0000, v183
	v_pk_add_f32 v[146:147], v[114:115], v[146:147]
	v_lshl_add_u64 v[114:115], s[14:15], 0, v[128:129]
	v_pk_add_f32 v[124:125], v[116:117], v[124:125]
	global_load_dwordx4 v[170:173], v143, s[44:45]
	s_waitcnt vmcnt(5)
	v_lshlrev_b32_e32 v148, 16, v184
	v_and_b32_e32 v149, 0xffff0000, v184
	v_lshlrev_b32_e32 v126, 16, v185
	v_and_b32_e32 v127, 0xffff0000, v185
	v_pk_add_f32 v[148:149], v[118:119], v[148:149]
	v_pk_add_f32 v[126:127], v[120:121], v[126:127]
	v_lshlrev_b32_e32 v128, 16, v186
	v_and_b32_e32 v129, 0xffff0000, v186
	v_lshlrev_b32_e32 v150, 16, v187
	v_and_b32_e32 v151, 0xffff0000, v187
	v_lshlrev_b32_e32 v156, 16, v188
	v_and_b32_e32 v157, 0xffff0000, v188
	v_lshlrev_b32_e32 v158, 16, v189
	v_and_b32_e32 v159, 0xffff0000, v189
	global_load_dwordx4 v[174:177], v204, s[78:79]
	s_waitcnt vmcnt(5)
	global_load_dwordx4 v[178:181], v205, s[78:79]
	s_waitcnt vmcnt(5)
	v_pk_fma_f32 v[118:119], v[190:191], v[156:157], v[148:149]
	v_pk_fma_f32 v[116:117], v[196:197], v[150:151], v[124:125]
	v_pk_fma_f32 v[124:125], v[194:195], v[128:129], v[146:147]
	v_pk_fma_f32 v[114:115], v[192:193], v[158:159], v[126:127]
	v_mul_f32_e32 v121, 0x3d372713, v118
	v_mul_f32_e32 v121, v118, v121
	v_fma_f32 v121, v118, v121, v118
	v_mul_f32_e32 v121, 0x3f4c422a, v121
	v_mul_f32_e32 v121, 0x4038aa3b, v121
	v_exp_f32_e32 v121, v121
	v_mul_f32_e32 v120, 0x3d372713, v124
	v_mul_f32_e32 v120, v124, v120
	v_fma_f32 v120, v124, v120, v124
	v_add_f32_e32 v121, 1.0, v121
	v_rcp_f32_e32 v126, v121
	v_mul_f32_e32 v121, 0x3d372713, v125
	v_mul_f32_e32 v121, v125, v121
	v_fma_f32 v121, v125, v121, v125
	v_mul_f32_e32 v120, 0x3f4c422a, v120
	v_mul_f32_e32 v121, 0x3f4c422a, v121
	v_mul_f32_e32 v120, 0x4038aa3b, v120
	v_mul_f32_e32 v121, 0x4038aa3b, v121
	v_exp_f32_e32 v120, v120
	v_exp_f32_e32 v121, v121
	v_pk_mul_f32 v[124:125], v[124:125], 0.5 op_sel_hi:[1,0]
	v_add_f32_e32 v120, 1.0, v120
	v_add_f32_e32 v121, 1.0, v121
	v_rcp_f32_e32 v120, v120
	v_rcp_f32_e32 v121, v121
	s_nop 0
	v_pk_fma_f32 v[120:121], v[120:121], 2.0, 1.0 op_sel_hi:[1,0,0] neg_lo:[1,0,0] neg_hi:[1,0,0]
	s_nop 0
	v_pk_add_f32 v[120:121], v[120:121], 1.0 op_sel_hi:[1,0]
	s_nop 0
	v_pk_mul_f32 v[120:121], v[124:125], v[120:121]
	v_mul_f32_e32 v124, 0x3d372713, v119
	v_mul_f32_e32 v124, v119, v124
	v_fma_f32 v124, v119, v124, v119
	v_mul_f32_e32 v124, 0x3f4c422a, v124
	v_mul_f32_e32 v124, 0x4038aa3b, v124
	v_exp_f32_e32 v124, v124
	v_pk_mul_f32 v[118:119], v[118:119], 0.5 op_sel_hi:[1,0]
	v_add_f32_e32 v124, 1.0, v124
	v_rcp_f32_e32 v127, v124
	s_nop 0
	v_pk_fma_f32 v[124:125], v[126:127], 2.0, 1.0 op_sel_hi:[1,0,0] neg_lo:[1,0,0] neg_hi:[1,0,0]
	s_nop 0
	v_pk_add_f32 v[124:125], v[124:125], 1.0 op_sel_hi:[1,0]
	s_nop 0
	v_pk_mul_f32 v[118:119], v[118:119], v[124:125]
	v_mul_f32_e32 v125, 0x3d372713, v114
	v_mul_f32_e32 v125, v114, v125
	v_fma_f32 v125, v114, v125, v114
	v_mul_f32_e32 v125, 0x3f4c422a, v125
	v_mul_f32_e32 v125, 0x4038aa3b, v125
	v_exp_f32_e32 v125, v125
	v_mul_f32_e32 v124, 0x3d372713, v116
	v_mul_f32_e32 v124, v116, v124
	v_fma_f32 v124, v116, v124, v116
	v_add_f32_e32 v125, 1.0, v125
	v_rcp_f32_e32 v126, v125
	v_mul_f32_e32 v125, 0x3d372713, v117
	v_mul_f32_e32 v125, v117, v125
	v_fma_f32 v125, v117, v125, v117
	v_mul_f32_e32 v124, 0x3f4c422a, v124
	v_mul_f32_e32 v125, 0x3f4c422a, v125
	v_mul_f32_e32 v124, 0x4038aa3b, v124
	v_mul_f32_e32 v125, 0x4038aa3b, v125
	v_exp_f32_e32 v124, v124
	v_exp_f32_e32 v125, v125
	v_pk_mul_f32 v[116:117], v[116:117], 0.5 op_sel_hi:[1,0]
	v_add_f32_e32 v124, 1.0, v124
	v_add_f32_e32 v125, 1.0, v125
	v_rcp_f32_e32 v124, v124
	v_rcp_f32_e32 v125, v125
	s_nop 0
	v_pk_fma_f32 v[124:125], v[124:125], 2.0, 1.0 op_sel_hi:[1,0,0] neg_lo:[1,0,0] neg_hi:[1,0,0]
	s_nop 0
	v_pk_add_f32 v[124:125], v[124:125], 1.0 op_sel_hi:[1,0]
	s_nop 0
	v_pk_mul_f32 v[116:117], v[116:117], v[124:125]
	v_mul_f32_e32 v124, 0x3d372713, v115
	v_mul_f32_e32 v124, v115, v124
	v_fma_f32 v124, v115, v124, v115
	v_mul_f32_e32 v124, 0x3f4c422a, v124
	v_mul_f32_e32 v124, 0x4038aa3b, v124
	v_exp_f32_e32 v124, v124
	v_pk_mul_f32 v[114:115], v[114:115], 0.5 op_sel_hi:[1,0]
	v_add_f32_e32 v124, 1.0, v124
	v_rcp_f32_e32 v127, v124
	s_nop 0
	v_pk_fma_f32 v[124:125], v[126:127], 2.0, 1.0 op_sel_hi:[1,0,0] neg_lo:[1,0,0] neg_hi:[1,0,0]
	s_nop 0
	v_pk_add_f32 v[124:125], v[124:125], 1.0 op_sel_hi:[1,0]
	v_lshl_add_u64 v[126:127], v[144:145], 0, v[122:123]
	v_pk_mul_f32 v[124:125], v[114:115], v[124:125]
	v_cvt_pk_bf16_f32 v115, v116, v117
	v_cvt_pk_bf16_f32 v116, v118, v119
	v_lshlrev_b64 v[118:119], 10, v[126:127]
	v_lshl_add_u64 v[118:119], s[16:17], 0, v[118:119]
	v_lshl_add_u64 v[118:119], v[118:119], 0, s[46:47]
	v_cvt_pk_bf16_f32 v114, v120, v121
	v_cvt_pk_bf16_f32 v117, v124, v125
	v_lshl_add_u64 v[118:119], v[118:119], 0, v[138:139]
	global_store_dwordx4 v[118:119], v[114:117], off
	global_load_dwordx4 v[182:185], v206, s[78:79]
	s_waitcnt vmcnt(5)
	s_nop 0
	global_load_dwordx4 v[186:189], v207, s[78:79]
	s_waitcnt vmcnt(5)
	v_add_u32_e32 v114, 16, v142
	v_ashrrev_i32_e32 v115, 31, v114
	v_lshlrev_b64 v[114:115], 5, v[114:115]
	v_lshl_add_u64 v[116:117], v[114:115], 0, s[60:61]
	v_lshl_add_u64 v[128:129], v[116:117], 0, v[140:141]
	v_lshlrev_b64 v[128:129], 5, v[128:129]
	v_or_b32_e32 v128, v128, v138
	v_lshl_add_u64 v[144:145], s[12:13], 0, v[128:129]
	global_load_dwordx4 v[190:193], v143, s[44:45] offset:16
	s_waitcnt vmcnt(5)
	v_lshlrev_b32_e32 v148, 16, v174
	v_and_b32_e32 v149, 0xffff0000, v174
	v_lshlrev_b32_e32 v144, 16, v175
	v_and_b32_e32 v145, 0xffff0000, v175
	v_pk_add_f32 v[148:149], v[106:107], v[148:149]
	v_lshl_add_u64 v[106:107], s[14:15], 0, v[128:129]
	v_pk_add_f32 v[144:145], v[108:109], v[144:145]
	global_load_dwordx4 v[194:197], v143, s[44:45]
	s_waitcnt vmcnt(5)
	v_lshlrev_b32_e32 v150, 16, v176
	v_and_b32_e32 v151, 0xffff0000, v176
	v_lshlrev_b32_e32 v146, 16, v177
	v_and_b32_e32 v147, 0xffff0000, v177
	v_pk_add_f32 v[110:111], v[110:111], v[150:151]
	v_pk_add_f32 v[112:113], v[112:113], v[146:147]
	v_lshlrev_b32_e32 v128, 16, v178
	v_and_b32_e32 v129, 0xffff0000, v178
	v_lshlrev_b32_e32 v106, 16, v179
	v_and_b32_e32 v107, 0xffff0000, v179
	v_lshlrev_b32_e32 v146, 16, v180
	v_and_b32_e32 v147, 0xffff0000, v180
	v_lshlrev_b32_e32 v108, 16, v181
	v_and_b32_e32 v109, 0xffff0000, v181
	v_pk_fma_f32 v[126:127], v[172:173], v[106:107], v[144:145]
	v_pk_fma_f32 v[106:107], v[200:201], v[108:109], v[112:113]
	v_pk_fma_f32 v[108:109], v[198:199], v[146:147], v[110:111]
	v_pk_fma_f32 v[124:125], v[170:171], v[128:129], v[148:149]
	v_mul_f32_e32 v111, 0x3d372713, v108
	v_mul_f32_e32 v113, 0x3d372713, v109
	v_mul_f32_e32 v111, v108, v111
	v_mul_f32_e32 v113, v109, v113
	v_fma_f32 v111, v108, v111, v108
	v_fma_f32 v113, v109, v113, v109
	v_mul_f32_e32 v111, 0x3f4c422a, v111
	v_mul_f32_e32 v113, 0x3f4c422a, v113
	v_mul_f32_e32 v111, 0x4038aa3b, v111
	v_mul_f32_e32 v113, 0x4038aa3b, v113
	v_exp_f32_e32 v111, v111
	v_exp_f32_e32 v113, v113
	v_mul_f32_e32 v110, 0x3d372713, v124
	v_mul_f32_e32 v110, v124, v110
	v_add_f32_e32 v111, 1.0, v111
	v_add_f32_e32 v113, 1.0, v113
	v_rcp_f32_e32 v112, v111
	v_mul_f32_e32 v111, 0x3d372713, v125
	v_rcp_f32_e32 v113, v113
	v_mul_f32_e32 v111, v125, v111
	v_fma_f32 v110, v124, v110, v124
	v_fma_f32 v111, v125, v111, v125
	v_mul_f32_e32 v110, 0x3f4c422a, v110
	v_mul_f32_e32 v111, 0x3f4c422a, v111
	v_mul_f32_e32 v110, 0x4038aa3b, v110
	v_mul_f32_e32 v111, 0x4038aa3b, v111
	v_pk_fma_f32 v[112:113], v[112:113], 2.0, 1.0 op_sel_hi:[1,0,0] neg_lo:[1,0,0] neg_hi:[1,0,0]
	v_exp_f32_e32 v110, v110
	v_exp_f32_e32 v111, v111
	v_pk_mul_f32 v[108:109], v[108:109], 0.5 op_sel_hi:[1,0]
	v_pk_add_f32 v[112:113], v[112:113], 1.0 op_sel_hi:[1,0]
	v_add_f32_e32 v110, 1.0, v110
	v_pk_mul_f32 v[108:109], v[108:109], v[112:113]
	v_mul_f32_e32 v113, 0x3d372713, v106
	v_mul_f32_e32 v113, v106, v113
	v_fma_f32 v113, v106, v113, v106
	v_add_f32_e32 v111, 1.0, v111
	v_mul_f32_e32 v113, 0x3f4c422a, v113
	v_rcp_f32_e32 v110, v110
	v_rcp_f32_e32 v111, v111
	v_mul_f32_e32 v113, 0x4038aa3b, v113
	v_exp_f32_e32 v113, v113
	v_pk_mul_f32 v[118:119], v[124:125], 0.5 op_sel_hi:[1,0]
	v_pk_fma_f32 v[110:111], v[110:111], 2.0, 1.0 op_sel_hi:[1,0,0] neg_lo:[1,0,0] neg_hi:[1,0,0]
	v_mul_f32_e32 v112, 0x3d372713, v126
	v_pk_add_f32 v[110:111], v[110:111], 1.0 op_sel_hi:[1,0]
	v_add_f32_e32 v113, 1.0, v113
	v_pk_mul_f32 v[110:111], v[118:119], v[110:111]
	v_rcp_f32_e32 v118, v113
	v_mul_f32_e32 v113, 0x3d372713, v127
	v_mul_f32_e32 v112, v126, v112
	v_mul_f32_e32 v113, v127, v113
	v_mul_f32_e32 v119, 0x3d372713, v107
	v_fma_f32 v112, v126, v112, v126
	v_fma_f32 v113, v127, v113, v127
	v_mul_f32_e32 v119, v107, v119
	v_mul_f32_e32 v112, 0x3f4c422a, v112
	v_mul_f32_e32 v113, 0x3f4c422a, v113
	v_fma_f32 v119, v107, v119, v107
	v_mul_f32_e32 v112, 0x4038aa3b, v112
	v_mul_f32_e32 v113, 0x4038aa3b, v113
	v_mul_f32_e32 v119, 0x3f4c422a, v119
	v_exp_f32_e32 v112, v112
	v_exp_f32_e32 v113, v113
	v_mul_f32_e32 v119, 0x4038aa3b, v119
	v_exp_f32_e32 v119, v119
	v_add_f32_e32 v112, 1.0, v112
	v_add_f32_e32 v113, 1.0, v113
	v_rcp_f32_e32 v112, v112
	v_rcp_f32_e32 v113, v113
	v_add_f32_e32 v119, 1.0, v119
	v_rcp_f32_e32 v119, v119
	v_pk_mul_f32 v[120:121], v[126:127], 0.5 op_sel_hi:[1,0]
	v_pk_fma_f32 v[112:113], v[112:113], 2.0, 1.0 op_sel_hi:[1,0,0] neg_lo:[1,0,0] neg_hi:[1,0,0]
	v_pk_mul_f32 v[106:107], v[106:107], 0.5 op_sel_hi:[1,0]
	v_pk_add_f32 v[112:113], v[112:113], 1.0 op_sel_hi:[1,0]
	v_pk_fma_f32 v[118:119], v[118:119], 2.0, 1.0 op_sel_hi:[1,0,0] neg_lo:[1,0,0] neg_hi:[1,0,0]
	v_pk_mul_f32 v[112:113], v[120:121], v[112:113]
	v_pk_add_f32 v[118:119], v[118:119], 1.0 op_sel_hi:[1,0]
	v_lshl_add_u64 v[120:121], v[114:115], 0, v[140:141]
	v_pk_mul_f32 v[118:119], v[106:107], v[118:119]
	v_cvt_pk_bf16_f32 v106, v110, v111
	v_lshlrev_b64 v[110:111], 10, v[120:121]
	v_lshl_add_u64 v[110:111], s[16:17], 0, v[110:111]
	v_lshl_add_u64 v[110:111], v[110:111], 0, s[46:47]
	v_cvt_pk_bf16_f32 v107, v112, v113
	v_cvt_pk_bf16_f32 v108, v108, v109
	v_cvt_pk_bf16_f32 v109, v118, v119
	v_lshl_add_u64 v[110:111], v[110:111], 0, v[138:139]
	global_store_dwordx4 v[110:111], v[106:109], off
	s_nop 1
	v_lshl_add_u64 v[106:107], v[116:117], 0, v[122:123]
	v_lshlrev_b64 v[110:111], 5, v[106:107]
	v_or_b32_e32 v110, v110, v138
	v_lshl_add_u64 v[106:107], s[12:13], 0, v[110:111]
	global_load_dwordx4 v[198:201], v143, s[44:45] offset:16
	s_waitcnt vmcnt(5)
	v_lshlrev_b32_e32 v112, 16, v182
	v_and_b32_e32 v113, 0xffff0000, v182
	v_lshlrev_b32_e32 v106, 16, v183
	v_and_b32_e32 v107, 0xffff0000, v183
	v_pk_add_f32 v[112:113], v[98:99], v[112:113]
	v_lshl_add_u64 v[98:99], s[14:15], 0, v[110:111]
	v_pk_add_f32 v[118:119], v[100:101], v[106:107]
	global_load_dwordx4 v[170:173], v143, s[44:45]
	s_waitcnt vmcnt(5)
	v_lshlrev_b32_e32 v116, 16, v184
	v_and_b32_e32 v117, 0xffff0000, v184
	v_lshlrev_b32_e32 v108, 16, v185
	v_and_b32_e32 v109, 0xffff0000, v185
	v_pk_add_f32 v[116:117], v[102:103], v[116:117]
	v_pk_add_f32 v[120:121], v[104:105], v[108:109]
	global_load_dwordx4 v[174:177], v208, s[78:79]
	s_waitcnt vmcnt(5)
	global_load_dwordx4 v[178:181], v209, s[78:79]
	s_waitcnt vmcnt(5)
	v_lshlrev_b32_e32 v124, 16, v188
	v_and_b32_e32 v125, 0xffff0000, v188
	v_lshlrev_b32_e32 v100, 16, v189
	v_and_b32_e32 v101, 0xffff0000, v189
	v_lshlrev_b32_e32 v110, 16, v186
	v_and_b32_e32 v111, 0xffff0000, v186
	v_pk_fma_f32 v[102:103], v[190:191], v[124:125], v[116:117]
	v_pk_fma_f32 v[100:101], v[192:193], v[100:101], v[120:121]
	v_mul_f32_e32 v105, 0x3d372713, v102
	v_mul_f32_e32 v105, v102, v105
	v_fma_f32 v105, v102, v105, v102
	v_mul_f32_e32 v105, 0x3f4c422a, v105
	v_mul_f32_e32 v105, 0x4038aa3b, v105
	v_exp_f32_e32 v105, v105
	v_lshlrev_b32_e32 v98, 16, v187
	v_and_b32_e32 v99, 0xffff0000, v187
	v_pk_fma_f32 v[106:107], v[194:195], v[110:111], v[112:113]
	v_add_f32_e32 v105, 1.0, v105
	v_pk_fma_f32 v[98:99], v[196:197], v[98:99], v[118:119]
	v_mul_f32_e32 v104, 0x3d372713, v106
	v_rcp_f32_e32 v108, v105
	v_mul_f32_e32 v105, 0x3d372713, v107
	v_mul_f32_e32 v104, v106, v104
	v_mul_f32_e32 v105, v107, v105
	v_fma_f32 v104, v106, v104, v106
	v_fma_f32 v105, v107, v105, v107
	v_mul_f32_e32 v104, 0x3f4c422a, v104
	v_mul_f32_e32 v105, 0x3f4c422a, v105
	v_mul_f32_e32 v104, 0x4038aa3b, v104
	v_mul_f32_e32 v105, 0x4038aa3b, v105
	v_exp_f32_e32 v104, v104
	v_exp_f32_e32 v105, v105
	v_pk_mul_f32 v[106:107], v[106:107], 0.5 op_sel_hi:[1,0]
	v_lshl_add_u64 v[110:111], v[114:115], 0, v[122:123]
	v_add_f32_e32 v104, 1.0, v104
	v_add_f32_e32 v105, 1.0, v105
	v_rcp_f32_e32 v104, v104
	v_rcp_f32_e32 v105, v105
	s_nop 0
	v_pk_fma_f32 v[104:105], v[104:105], 2.0, 1.0 op_sel_hi:[1,0,0] neg_lo:[1,0,0] neg_hi:[1,0,0]
	s_nop 0
	v_pk_add_f32 v[104:105], v[104:105], 1.0 op_sel_hi:[1,0]
	s_nop 0
	v_pk_mul_f32 v[104:105], v[106:107], v[104:105]
	v_mul_f32_e32 v106, 0x3d372713, v103
	v_mul_f32_e32 v106, v103, v106
	v_fma_f32 v106, v103, v106, v103
	v_mul_f32_e32 v106, 0x3f4c422a, v106
	v_mul_f32_e32 v106, 0x4038aa3b, v106
	v_exp_f32_e32 v106, v106
	v_pk_mul_f32 v[102:103], v[102:103], 0.5 op_sel_hi:[1,0]
	v_add_f32_e32 v106, 1.0, v106
	v_rcp_f32_e32 v109, v106
	s_nop 0
	v_pk_fma_f32 v[106:107], v[108:109], 2.0, 1.0 op_sel_hi:[1,0,0] neg_lo:[1,0,0] neg_hi:[1,0,0]
	s_nop 0
	v_pk_add_f32 v[106:107], v[106:107], 1.0 op_sel_hi:[1,0]
	s_nop 0
	v_pk_mul_f32 v[102:103], v[102:103], v[106:107]
	v_mul_f32_e32 v107, 0x3d372713, v100
	v_mul_f32_e32 v107, v100, v107
	v_fma_f32 v107, v100, v107, v100
	v_mul_f32_e32 v107, 0x3f4c422a, v107
	v_mul_f32_e32 v107, 0x4038aa3b, v107
	v_exp_f32_e32 v107, v107
	v_mul_f32_e32 v106, 0x3d372713, v98
	v_mul_f32_e32 v106, v98, v106
	v_fma_f32 v106, v98, v106, v98
	v_add_f32_e32 v107, 1.0, v107
	v_rcp_f32_e32 v108, v107
	v_mul_f32_e32 v107, 0x3d372713, v99
	v_mul_f32_e32 v107, v99, v107
	v_fma_f32 v107, v99, v107, v99
	v_mul_f32_e32 v106, 0x3f4c422a, v106
	v_mul_f32_e32 v107, 0x3f4c422a, v107
	v_mul_f32_e32 v106, 0x4038aa3b, v106
	v_mul_f32_e32 v107, 0x4038aa3b, v107
	v_exp_f32_e32 v106, v106
	v_exp_f32_e32 v107, v107
	v_pk_mul_f32 v[98:99], v[98:99], 0.5 op_sel_hi:[1,0]
	v_add_f32_e32 v106, 1.0, v106
	v_add_f32_e32 v107, 1.0, v107
	v_rcp_f32_e32 v106, v106
	v_rcp_f32_e32 v107, v107
	s_nop 0
	v_pk_fma_f32 v[106:107], v[106:107], 2.0, 1.0 op_sel_hi:[1,0,0] neg_lo:[1,0,0] neg_hi:[1,0,0]
	s_nop 0
	v_pk_add_f32 v[106:107], v[106:107], 1.0 op_sel_hi:[1,0]
	s_nop 0
	v_pk_mul_f32 v[106:107], v[98:99], v[106:107]
	v_mul_f32_e32 v98, 0x3d372713, v101
	v_mul_f32_e32 v98, v101, v98
	v_fma_f32 v98, v101, v98, v101
	v_mul_f32_e32 v98, 0x3f4c422a, v98
	v_mul_f32_e32 v98, 0x4038aa3b, v98
	v_exp_f32_e32 v98, v98
	v_pk_mul_f32 v[100:101], v[100:101], 0.5 op_sel_hi:[1,0]
	v_add_f32_e32 v98, 1.0, v98
	v_rcp_f32_e32 v109, v98
	s_nop 0
	v_pk_fma_f32 v[98:99], v[108:109], 2.0, 1.0 op_sel_hi:[1,0,0] neg_lo:[1,0,0] neg_hi:[1,0,0]
	s_nop 0
	v_pk_add_f32 v[98:99], v[98:99], 1.0 op_sel_hi:[1,0]
	s_nop 0
	v_pk_mul_f32 v[108:109], v[100:101], v[98:99]
	v_cvt_pk_bf16_f32 v100, v102, v103
	v_lshlrev_b64 v[102:103], 10, v[110:111]
	v_lshl_add_u64 v[102:103], s[16:17], 0, v[102:103]
	v_lshl_add_u64 v[102:103], v[102:103], 0, s[46:47]
	v_cvt_pk_bf16_f32 v98, v104, v105
	v_cvt_pk_bf16_f32 v99, v106, v107
	v_cvt_pk_bf16_f32 v101, v108, v109
	v_lshl_add_u64 v[102:103], v[102:103], 0, v[138:139]
	global_store_dwordx4 v[102:103], v[98:101], off
	global_load_dwordx4 v[182:185], v210, s[78:79]
	s_waitcnt vmcnt(5)
	s_nop 0
	global_load_dwordx4 v[186:189], v211, s[78:79]
	s_waitcnt vmcnt(5)
	v_add_u32_e32 v98, 32, v142
	v_ashrrev_i32_e32 v99, 31, v98
	v_lshlrev_b64 v[98:99], 5, v[98:99]
	v_lshl_add_u64 v[100:101], v[98:99], 0, s[60:61]
	v_lshl_add_u64 v[110:111], v[100:101], 0, v[140:141]
	v_lshlrev_b64 v[114:115], 5, v[110:111]
	v_or_b32_e32 v114, v114, v138
	v_lshl_add_u64 v[110:111], s[12:13], 0, v[114:115]
	global_load_dwordx4 v[190:193], v143, s[44:45] offset:16
	s_waitcnt vmcnt(5)
	v_lshlrev_b32_e32 v116, 16, v174
	v_and_b32_e32 v117, 0xffff0000, v174
	v_lshlrev_b32_e32 v110, 16, v175
	v_and_b32_e32 v111, 0xffff0000, v175
	v_pk_add_f32 v[116:117], v[90:91], v[116:117]
	v_lshl_add_u64 v[90:91], s[14:15], 0, v[114:115]
	v_pk_add_f32 v[110:111], v[92:93], v[110:111]
	global_load_dwordx4 v[194:197], v143, s[44:45]
	s_waitcnt vmcnt(5)
	v_lshlrev_b32_e32 v118, 16, v176
	v_and_b32_e32 v119, 0xffff0000, v176
	v_lshlrev_b32_e32 v112, 16, v177
	v_and_b32_e32 v113, 0xffff0000, v177
	v_pk_add_f32 v[94:95], v[94:95], v[118:119]
	v_pk_add_f32 v[96:97], v[96:97], v[112:113]
	v_lshlrev_b32_e32 v112, 16, v178
	v_and_b32_e32 v113, 0xffff0000, v178
	v_lshlrev_b32_e32 v90, 16, v179
	v_and_b32_e32 v91, 0xffff0000, v179
	v_lshlrev_b32_e32 v114, 16, v180
	v_and_b32_e32 v115, 0xffff0000, v180
	v_lshlrev_b32_e32 v92, 16, v181
	v_and_b32_e32 v93, 0xffff0000, v181
	v_pk_fma_f32 v[108:109], v[172:173], v[90:91], v[110:111]
	v_pk_fma_f32 v[90:91], v[200:201], v[92:93], v[96:97]
	v_pk_fma_f32 v[92:93], v[198:199], v[114:115], v[94:95]
	v_pk_fma_f32 v[106:107], v[170:171], v[112:113], v[116:117]
	v_mul_f32_e32 v95, 0x3d372713, v92
	v_mul_f32_e32 v97, 0x3d372713, v93
	v_mul_f32_e32 v95, v92, v95
	v_mul_f32_e32 v97, v93, v97
	v_fma_f32 v95, v92, v95, v92
	v_fma_f32 v97, v93, v97, v93
	v_mul_f32_e32 v95, 0x3f4c422a, v95
	v_mul_f32_e32 v97, 0x3f4c422a, v97
	v_mul_f32_e32 v95, 0x4038aa3b, v95
	v_mul_f32_e32 v97, 0x4038aa3b, v97
	v_exp_f32_e32 v95, v95
	v_exp_f32_e32 v97, v97
	v_mul_f32_e32 v94, 0x3d372713, v106
	v_mul_f32_e32 v94, v106, v94
	v_add_f32_e32 v95, 1.0, v95
	v_add_f32_e32 v97, 1.0, v97
	v_rcp_f32_e32 v96, v95
	v_mul_f32_e32 v95, 0x3d372713, v107
	v_rcp_f32_e32 v97, v97
	v_mul_f32_e32 v95, v107, v95
	v_fma_f32 v94, v106, v94, v106
	v_fma_f32 v95, v107, v95, v107
	v_mul_f32_e32 v94, 0x3f4c422a, v94
	v_mul_f32_e32 v95, 0x3f4c422a, v95
	v_mul_f32_e32 v94, 0x4038aa3b, v94
	v_mul_f32_e32 v95, 0x4038aa3b, v95
	v_pk_fma_f32 v[96:97], v[96:97], 2.0, 1.0 op_sel_hi:[1,0,0] neg_lo:[1,0,0] neg_hi:[1,0,0]
	v_exp_f32_e32 v94, v94
	v_exp_f32_e32 v95, v95
	v_pk_mul_f32 v[92:93], v[92:93], 0.5 op_sel_hi:[1,0]
	v_pk_add_f32 v[96:97], v[96:97], 1.0 op_sel_hi:[1,0]
	v_add_f32_e32 v94, 1.0, v94
	v_pk_mul_f32 v[92:93], v[92:93], v[96:97]
	v_mul_f32_e32 v97, 0x3d372713, v90
	v_mul_f32_e32 v97, v90, v97
	v_fma_f32 v97, v90, v97, v90
	v_add_f32_e32 v95, 1.0, v95
	v_mul_f32_e32 v97, 0x3f4c422a, v97
	v_rcp_f32_e32 v94, v94
	v_rcp_f32_e32 v95, v95
	v_mul_f32_e32 v97, 0x4038aa3b, v97
	v_exp_f32_e32 v97, v97
	v_pk_mul_f32 v[102:103], v[106:107], 0.5 op_sel_hi:[1,0]
	v_pk_fma_f32 v[94:95], v[94:95], 2.0, 1.0 op_sel_hi:[1,0,0] neg_lo:[1,0,0] neg_hi:[1,0,0]
	v_mul_f32_e32 v96, 0x3d372713, v108
	v_pk_add_f32 v[94:95], v[94:95], 1.0 op_sel_hi:[1,0]
	v_add_f32_e32 v97, 1.0, v97
	v_pk_mul_f32 v[94:95], v[102:103], v[94:95]
	v_rcp_f32_e32 v102, v97
	v_mul_f32_e32 v97, 0x3d372713, v109
	v_mul_f32_e32 v96, v108, v96
	v_mul_f32_e32 v97, v109, v97
	v_mul_f32_e32 v103, 0x3d372713, v91
	v_fma_f32 v96, v108, v96, v108
	v_fma_f32 v97, v109, v97, v109
	v_mul_f32_e32 v103, v91, v103
	v_mul_f32_e32 v96, 0x3f4c422a, v96
	v_mul_f32_e32 v97, 0x3f4c422a, v97
	v_fma_f32 v103, v91, v103, v91
	v_mul_f32_e32 v96, 0x4038aa3b, v96
	v_mul_f32_e32 v97, 0x4038aa3b, v97
	v_mul_f32_e32 v103, 0x3f4c422a, v103
	v_exp_f32_e32 v96, v96
	v_exp_f32_e32 v97, v97
	v_mul_f32_e32 v103, 0x4038aa3b, v103
	v_exp_f32_e32 v103, v103
	v_add_f32_e32 v96, 1.0, v96
	v_add_f32_e32 v97, 1.0, v97
	v_rcp_f32_e32 v96, v96
	v_rcp_f32_e32 v97, v97
	v_add_f32_e32 v103, 1.0, v103
	v_rcp_f32_e32 v103, v103
	v_pk_mul_f32 v[104:105], v[108:109], 0.5 op_sel_hi:[1,0]
	v_pk_fma_f32 v[96:97], v[96:97], 2.0, 1.0 op_sel_hi:[1,0,0] neg_lo:[1,0,0] neg_hi:[1,0,0]
	v_pk_mul_f32 v[90:91], v[90:91], 0.5 op_sel_hi:[1,0]
	v_pk_add_f32 v[96:97], v[96:97], 1.0 op_sel_hi:[1,0]
	v_pk_fma_f32 v[102:103], v[102:103], 2.0, 1.0 op_sel_hi:[1,0,0] neg_lo:[1,0,0] neg_hi:[1,0,0]
	v_pk_mul_f32 v[96:97], v[104:105], v[96:97]
	v_pk_add_f32 v[102:103], v[102:103], 1.0 op_sel_hi:[1,0]
	v_lshl_add_u64 v[104:105], v[98:99], 0, v[140:141]
	v_pk_mul_f32 v[102:103], v[90:91], v[102:103]
	v_cvt_pk_bf16_f32 v90, v94, v95
	v_lshlrev_b64 v[94:95], 10, v[104:105]
	v_lshl_add_u64 v[94:95], s[16:17], 0, v[94:95]
	v_lshl_add_u64 v[94:95], v[94:95], 0, s[46:47]
	v_cvt_pk_bf16_f32 v91, v96, v97
	v_cvt_pk_bf16_f32 v92, v92, v93
	v_cvt_pk_bf16_f32 v93, v102, v103
	v_lshl_add_u64 v[94:95], v[94:95], 0, v[138:139]
	global_store_dwordx4 v[94:95], v[90:93], off
	s_nop 1
	v_lshl_add_u64 v[90:91], v[100:101], 0, v[122:123]
	v_lshlrev_b64 v[94:95], 5, v[90:91]
	v_or_b32_e32 v94, v94, v138
	v_lshl_add_u64 v[90:91], s[12:13], 0, v[94:95]
	global_load_dwordx4 v[198:201], v143, s[44:45] offset:16
	s_waitcnt vmcnt(5)
	v_lshlrev_b32_e32 v96, 16, v182
	v_and_b32_e32 v97, 0xffff0000, v182
	v_lshlrev_b32_e32 v90, 16, v183
	v_and_b32_e32 v91, 0xffff0000, v183
	v_pk_add_f32 v[96:97], v[82:83], v[96:97]
	v_lshl_add_u64 v[82:83], s[14:15], 0, v[94:95]
	v_pk_add_f32 v[102:103], v[84:85], v[90:91]
	global_load_dwordx4 v[170:173], v143, s[44:45]
	s_waitcnt vmcnt(5)
	v_lshlrev_b32_e32 v100, 16, v184
	v_and_b32_e32 v101, 0xffff0000, v184
	v_lshlrev_b32_e32 v92, 16, v185
	v_and_b32_e32 v93, 0xffff0000, v185
	v_pk_add_f32 v[100:101], v[86:87], v[100:101]
	v_pk_add_f32 v[104:105], v[88:89], v[92:93]
	global_load_dwordx4 v[174:177], v212, s[78:79]
	s_waitcnt vmcnt(5)
	global_load_dwordx4 v[178:181], v213, s[78:79]
	s_waitcnt vmcnt(5)
	v_lshlrev_b32_e32 v106, 16, v188
	v_and_b32_e32 v107, 0xffff0000, v188
	v_lshlrev_b32_e32 v84, 16, v189
	v_and_b32_e32 v85, 0xffff0000, v189
	v_lshlrev_b32_e32 v94, 16, v186
	v_and_b32_e32 v95, 0xffff0000, v186
	v_pk_fma_f32 v[86:87], v[190:191], v[106:107], v[100:101]
	v_pk_fma_f32 v[84:85], v[192:193], v[84:85], v[104:105]
	v_mul_f32_e32 v89, 0x3d372713, v86
	v_mul_f32_e32 v89, v86, v89
	v_fma_f32 v89, v86, v89, v86
	v_mul_f32_e32 v89, 0x3f4c422a, v89
	v_mul_f32_e32 v89, 0x4038aa3b, v89
	v_exp_f32_e32 v89, v89
	v_lshlrev_b32_e32 v82, 16, v187
	v_and_b32_e32 v83, 0xffff0000, v187
	v_pk_fma_f32 v[90:91], v[194:195], v[94:95], v[96:97]
	v_add_f32_e32 v89, 1.0, v89
	v_pk_fma_f32 v[82:83], v[196:197], v[82:83], v[102:103]
	v_mul_f32_e32 v88, 0x3d372713, v90
	v_rcp_f32_e32 v92, v89
	v_mul_f32_e32 v89, 0x3d372713, v91
	v_mul_f32_e32 v88, v90, v88
	v_mul_f32_e32 v89, v91, v89
	v_fma_f32 v88, v90, v88, v90
	v_fma_f32 v89, v91, v89, v91
	v_mul_f32_e32 v88, 0x3f4c422a, v88
	v_mul_f32_e32 v89, 0x3f4c422a, v89
	v_mul_f32_e32 v88, 0x4038aa3b, v88
	v_mul_f32_e32 v89, 0x4038aa3b, v89
	v_exp_f32_e32 v88, v88
	v_exp_f32_e32 v89, v89
	v_pk_mul_f32 v[90:91], v[90:91], 0.5 op_sel_hi:[1,0]
	v_lshl_add_u64 v[94:95], v[98:99], 0, v[122:123]
	v_add_f32_e32 v88, 1.0, v88
	v_add_f32_e32 v89, 1.0, v89
	v_rcp_f32_e32 v88, v88
	v_rcp_f32_e32 v89, v89
	s_nop 0
	v_pk_fma_f32 v[88:89], v[88:89], 2.0, 1.0 op_sel_hi:[1,0,0] neg_lo:[1,0,0] neg_hi:[1,0,0]
	s_nop 0
	v_pk_add_f32 v[88:89], v[88:89], 1.0 op_sel_hi:[1,0]
	s_nop 0
	v_pk_mul_f32 v[88:89], v[90:91], v[88:89]
	v_mul_f32_e32 v90, 0x3d372713, v87
	v_mul_f32_e32 v90, v87, v90
	v_fma_f32 v90, v87, v90, v87
	v_mul_f32_e32 v90, 0x3f4c422a, v90
	v_mul_f32_e32 v90, 0x4038aa3b, v90
	v_exp_f32_e32 v90, v90
	v_pk_mul_f32 v[86:87], v[86:87], 0.5 op_sel_hi:[1,0]
	v_add_f32_e32 v90, 1.0, v90
	v_rcp_f32_e32 v93, v90
	s_nop 0
	v_pk_fma_f32 v[90:91], v[92:93], 2.0, 1.0 op_sel_hi:[1,0,0] neg_lo:[1,0,0] neg_hi:[1,0,0]
	s_nop 0
	v_pk_add_f32 v[90:91], v[90:91], 1.0 op_sel_hi:[1,0]
	s_nop 0
	v_pk_mul_f32 v[86:87], v[86:87], v[90:91]
	v_mul_f32_e32 v91, 0x3d372713, v84
	v_mul_f32_e32 v91, v84, v91
	v_fma_f32 v91, v84, v91, v84
	v_mul_f32_e32 v91, 0x3f4c422a, v91
	v_mul_f32_e32 v91, 0x4038aa3b, v91
	v_exp_f32_e32 v91, v91
	v_mul_f32_e32 v90, 0x3d372713, v82
	v_mul_f32_e32 v90, v82, v90
	v_fma_f32 v90, v82, v90, v82
	v_add_f32_e32 v91, 1.0, v91
	v_rcp_f32_e32 v92, v91
	v_mul_f32_e32 v91, 0x3d372713, v83
	v_mul_f32_e32 v91, v83, v91
	v_fma_f32 v91, v83, v91, v83
	v_mul_f32_e32 v90, 0x3f4c422a, v90
	v_mul_f32_e32 v91, 0x3f4c422a, v91
	v_mul_f32_e32 v90, 0x4038aa3b, v90
	v_mul_f32_e32 v91, 0x4038aa3b, v91
	v_exp_f32_e32 v90, v90
	v_exp_f32_e32 v91, v91
	v_pk_mul_f32 v[82:83], v[82:83], 0.5 op_sel_hi:[1,0]
	v_add_f32_e32 v90, 1.0, v90
	v_add_f32_e32 v91, 1.0, v91
	v_rcp_f32_e32 v90, v90
	v_rcp_f32_e32 v91, v91
	s_nop 0
	v_pk_fma_f32 v[90:91], v[90:91], 2.0, 1.0 op_sel_hi:[1,0,0] neg_lo:[1,0,0] neg_hi:[1,0,0]
	s_nop 0
	v_pk_add_f32 v[90:91], v[90:91], 1.0 op_sel_hi:[1,0]
	s_nop 0
	v_pk_mul_f32 v[90:91], v[82:83], v[90:91]
	v_mul_f32_e32 v82, 0x3d372713, v85
	v_mul_f32_e32 v82, v85, v82
	v_fma_f32 v82, v85, v82, v85
	v_mul_f32_e32 v82, 0x3f4c422a, v82
	v_mul_f32_e32 v82, 0x4038aa3b, v82
	v_exp_f32_e32 v82, v82
	v_pk_mul_f32 v[84:85], v[84:85], 0.5 op_sel_hi:[1,0]
	v_add_f32_e32 v82, 1.0, v82
	v_rcp_f32_e32 v93, v82
	s_nop 0
	v_pk_fma_f32 v[82:83], v[92:93], 2.0, 1.0 op_sel_hi:[1,0,0] neg_lo:[1,0,0] neg_hi:[1,0,0]
	s_nop 0
	v_pk_add_f32 v[82:83], v[82:83], 1.0 op_sel_hi:[1,0]
	s_nop 0
	v_pk_mul_f32 v[92:93], v[84:85], v[82:83]
	v_cvt_pk_bf16_f32 v84, v86, v87
	v_lshlrev_b64 v[86:87], 10, v[94:95]
	v_lshl_add_u64 v[86:87], s[16:17], 0, v[86:87]
	v_lshl_add_u64 v[86:87], v[86:87], 0, s[46:47]
	v_cvt_pk_bf16_f32 v82, v88, v89
	v_cvt_pk_bf16_f32 v83, v90, v91
	v_cvt_pk_bf16_f32 v85, v92, v93
	v_lshl_add_u64 v[86:87], v[86:87], 0, v[138:139]
	global_store_dwordx4 v[86:87], v[82:85], off
	global_load_dwordx4 v[182:185], v214, s[78:79]
	s_waitcnt vmcnt(5)
	s_nop 0
	global_load_dwordx4 v[186:189], v215, s[78:79]
	s_waitcnt vmcnt(5)
	v_add_u32_e32 v82, 48, v142
	v_ashrrev_i32_e32 v83, 31, v82
	v_lshlrev_b64 v[82:83], 5, v[82:83]
	v_lshl_add_u64 v[84:85], v[82:83], 0, s[60:61]
	v_lshl_add_u64 v[94:95], v[84:85], 0, v[140:141]
	v_lshlrev_b64 v[98:99], 5, v[94:95]
	v_or_b32_e32 v98, v98, v138
	v_lshl_add_u64 v[94:95], s[12:13], 0, v[98:99]
	global_load_dwordx4 v[190:193], v143, s[44:45] offset:16
	s_waitcnt vmcnt(5)
	v_lshlrev_b32_e32 v100, 16, v174
	v_and_b32_e32 v101, 0xffff0000, v174
	v_lshlrev_b32_e32 v94, 16, v175
	v_and_b32_e32 v95, 0xffff0000, v175
	v_pk_add_f32 v[100:101], v[74:75], v[100:101]
	v_lshl_add_u64 v[74:75], s[14:15], 0, v[98:99]
	v_pk_add_f32 v[94:95], v[76:77], v[94:95]
	global_load_dwordx4 v[194:197], v143, s[44:45]
	s_waitcnt vmcnt(5)
	v_lshlrev_b32_e32 v102, 16, v176
	v_and_b32_e32 v103, 0xffff0000, v176
	v_lshlrev_b32_e32 v96, 16, v177
	v_and_b32_e32 v97, 0xffff0000, v177
	v_pk_add_f32 v[78:79], v[78:79], v[102:103]
	v_pk_add_f32 v[80:81], v[80:81], v[96:97]
	v_lshlrev_b32_e32 v96, 16, v178
	v_and_b32_e32 v97, 0xffff0000, v178
	v_lshlrev_b32_e32 v74, 16, v179
	v_and_b32_e32 v75, 0xffff0000, v179
	v_lshlrev_b32_e32 v98, 16, v180
	v_and_b32_e32 v99, 0xffff0000, v180
	v_lshlrev_b32_e32 v76, 16, v181
	v_and_b32_e32 v77, 0xffff0000, v181
	v_pk_fma_f32 v[92:93], v[172:173], v[74:75], v[94:95]
	v_pk_fma_f32 v[74:75], v[200:201], v[76:77], v[80:81]
	v_pk_fma_f32 v[76:77], v[198:199], v[98:99], v[78:79]
	v_pk_fma_f32 v[90:91], v[170:171], v[96:97], v[100:101]
	v_mul_f32_e32 v79, 0x3d372713, v76
	v_mul_f32_e32 v81, 0x3d372713, v77
	v_mul_f32_e32 v79, v76, v79
	v_mul_f32_e32 v81, v77, v81
	v_fma_f32 v79, v76, v79, v76
	v_fma_f32 v81, v77, v81, v77
	v_mul_f32_e32 v79, 0x3f4c422a, v79
	v_mul_f32_e32 v81, 0x3f4c422a, v81
	v_mul_f32_e32 v79, 0x4038aa3b, v79
	v_mul_f32_e32 v81, 0x4038aa3b, v81
	v_exp_f32_e32 v79, v79
	v_exp_f32_e32 v81, v81
	v_mul_f32_e32 v78, 0x3d372713, v90
	v_mul_f32_e32 v78, v90, v78
	v_add_f32_e32 v79, 1.0, v79
	v_add_f32_e32 v81, 1.0, v81
	v_rcp_f32_e32 v80, v79
	v_mul_f32_e32 v79, 0x3d372713, v91
	v_rcp_f32_e32 v81, v81
	v_mul_f32_e32 v79, v91, v79
	v_fma_f32 v78, v90, v78, v90
	v_fma_f32 v79, v91, v79, v91
	v_mul_f32_e32 v78, 0x3f4c422a, v78
	v_mul_f32_e32 v79, 0x3f4c422a, v79
	v_mul_f32_e32 v78, 0x4038aa3b, v78
	v_mul_f32_e32 v79, 0x4038aa3b, v79
	v_pk_fma_f32 v[80:81], v[80:81], 2.0, 1.0 op_sel_hi:[1,0,0] neg_lo:[1,0,0] neg_hi:[1,0,0]
	v_exp_f32_e32 v78, v78
	v_exp_f32_e32 v79, v79
	v_pk_mul_f32 v[76:77], v[76:77], 0.5 op_sel_hi:[1,0]
	v_pk_add_f32 v[80:81], v[80:81], 1.0 op_sel_hi:[1,0]
	v_add_f32_e32 v78, 1.0, v78
	v_pk_mul_f32 v[76:77], v[76:77], v[80:81]
	v_mul_f32_e32 v81, 0x3d372713, v74
	v_mul_f32_e32 v81, v74, v81
	v_fma_f32 v81, v74, v81, v74
	v_add_f32_e32 v79, 1.0, v79
	v_mul_f32_e32 v81, 0x3f4c422a, v81
	v_rcp_f32_e32 v78, v78
	v_rcp_f32_e32 v79, v79
	v_mul_f32_e32 v81, 0x4038aa3b, v81
	v_exp_f32_e32 v81, v81
	v_pk_mul_f32 v[86:87], v[90:91], 0.5 op_sel_hi:[1,0]
	v_pk_fma_f32 v[78:79], v[78:79], 2.0, 1.0 op_sel_hi:[1,0,0] neg_lo:[1,0,0] neg_hi:[1,0,0]
	v_mul_f32_e32 v80, 0x3d372713, v92
	v_pk_add_f32 v[78:79], v[78:79], 1.0 op_sel_hi:[1,0]
	v_add_f32_e32 v81, 1.0, v81
	v_pk_mul_f32 v[78:79], v[86:87], v[78:79]
	v_rcp_f32_e32 v86, v81
	v_mul_f32_e32 v81, 0x3d372713, v93
	v_mul_f32_e32 v80, v92, v80
	v_mul_f32_e32 v81, v93, v81
	v_mul_f32_e32 v87, 0x3d372713, v75
	v_fma_f32 v80, v92, v80, v92
	v_fma_f32 v81, v93, v81, v93
	v_mul_f32_e32 v87, v75, v87
	v_mul_f32_e32 v80, 0x3f4c422a, v80
	v_mul_f32_e32 v81, 0x3f4c422a, v81
	v_fma_f32 v87, v75, v87, v75
	v_mul_f32_e32 v80, 0x4038aa3b, v80
	v_mul_f32_e32 v81, 0x4038aa3b, v81
	v_mul_f32_e32 v87, 0x3f4c422a, v87
	v_exp_f32_e32 v80, v80
	v_exp_f32_e32 v81, v81
	v_mul_f32_e32 v87, 0x4038aa3b, v87
	v_exp_f32_e32 v87, v87
	v_add_f32_e32 v80, 1.0, v80
	v_add_f32_e32 v81, 1.0, v81
	v_rcp_f32_e32 v80, v80
	v_rcp_f32_e32 v81, v81
	v_add_f32_e32 v87, 1.0, v87
	v_rcp_f32_e32 v87, v87
	v_pk_mul_f32 v[88:89], v[92:93], 0.5 op_sel_hi:[1,0]
	v_pk_fma_f32 v[80:81], v[80:81], 2.0, 1.0 op_sel_hi:[1,0,0] neg_lo:[1,0,0] neg_hi:[1,0,0]
	v_pk_mul_f32 v[74:75], v[74:75], 0.5 op_sel_hi:[1,0]
	v_pk_add_f32 v[80:81], v[80:81], 1.0 op_sel_hi:[1,0]
	v_pk_fma_f32 v[86:87], v[86:87], 2.0, 1.0 op_sel_hi:[1,0,0] neg_lo:[1,0,0] neg_hi:[1,0,0]
	v_pk_mul_f32 v[80:81], v[88:89], v[80:81]
	v_pk_add_f32 v[86:87], v[86:87], 1.0 op_sel_hi:[1,0]
	v_lshl_add_u64 v[88:89], v[82:83], 0, v[140:141]
	v_pk_mul_f32 v[86:87], v[74:75], v[86:87]
	v_cvt_pk_bf16_f32 v74, v78, v79
	v_lshlrev_b64 v[78:79], 10, v[88:89]
	v_lshl_add_u64 v[78:79], s[16:17], 0, v[78:79]
	v_lshl_add_u64 v[78:79], v[78:79], 0, s[46:47]
	v_cvt_pk_bf16_f32 v75, v80, v81
	v_cvt_pk_bf16_f32 v76, v76, v77
	v_cvt_pk_bf16_f32 v77, v86, v87
	v_lshl_add_u64 v[78:79], v[78:79], 0, v[138:139]
	global_store_dwordx4 v[78:79], v[74:77], off
	s_nop 1
	v_lshl_add_u64 v[74:75], v[84:85], 0, v[122:123]
	v_lshlrev_b64 v[78:79], 5, v[74:75]
	v_or_b32_e32 v78, v78, v138
	v_lshl_add_u64 v[74:75], s[12:13], 0, v[78:79]
	global_load_dwordx4 v[198:201], v216, s[78:79]
	s_waitcnt vmcnt(5)
	v_lshlrev_b32_e32 v80, 16, v182
	v_and_b32_e32 v81, 0xffff0000, v182
	v_lshlrev_b32_e32 v74, 16, v183
	v_and_b32_e32 v75, 0xffff0000, v183
	v_pk_add_f32 v[80:81], v[66:67], v[80:81]
	v_lshl_add_u64 v[66:67], s[14:15], 0, v[78:79]
	v_pk_add_f32 v[86:87], v[68:69], v[74:75]
	global_load_dwordx4 v[170:173], v217, s[78:79]
	s_waitcnt vmcnt(5)
	v_lshlrev_b32_e32 v84, 16, v184
	v_and_b32_e32 v85, 0xffff0000, v184
	v_lshlrev_b32_e32 v76, 16, v185
	v_and_b32_e32 v77, 0xffff0000, v185
	v_pk_add_f32 v[84:85], v[70:71], v[84:85]
	v_pk_add_f32 v[88:89], v[72:73], v[76:77]
	global_load_dwordx4 v[174:177], v143, s[44:45] offset:16
	s_waitcnt vmcnt(5)
	global_load_dwordx4 v[178:181], v143, s[44:45]
	s_waitcnt vmcnt(5)
	v_lshlrev_b32_e32 v90, 16, v188
	v_and_b32_e32 v91, 0xffff0000, v188
	v_lshlrev_b32_e32 v68, 16, v189
	v_and_b32_e32 v69, 0xffff0000, v189
	v_lshlrev_b32_e32 v78, 16, v186
	v_and_b32_e32 v79, 0xffff0000, v186
	v_pk_fma_f32 v[70:71], v[190:191], v[90:91], v[84:85]
	v_pk_fma_f32 v[68:69], v[192:193], v[68:69], v[88:89]
	v_mul_f32_e32 v73, 0x3d372713, v70
	v_mul_f32_e32 v73, v70, v73
	v_fma_f32 v73, v70, v73, v70
	v_mul_f32_e32 v73, 0x3f4c422a, v73
	v_mul_f32_e32 v73, 0x4038aa3b, v73
	v_exp_f32_e32 v73, v73
	v_lshlrev_b32_e32 v66, 16, v187
	v_and_b32_e32 v67, 0xffff0000, v187
	v_pk_fma_f32 v[74:75], v[194:195], v[78:79], v[80:81]
	v_add_f32_e32 v73, 1.0, v73
	v_pk_fma_f32 v[66:67], v[196:197], v[66:67], v[86:87]
	v_mul_f32_e32 v72, 0x3d372713, v74
	v_rcp_f32_e32 v76, v73
	v_mul_f32_e32 v73, 0x3d372713, v75
	v_mul_f32_e32 v72, v74, v72
	v_mul_f32_e32 v73, v75, v73
	v_fma_f32 v72, v74, v72, v74
	v_fma_f32 v73, v75, v73, v75
	v_mul_f32_e32 v72, 0x3f4c422a, v72
	v_mul_f32_e32 v73, 0x3f4c422a, v73
	v_mul_f32_e32 v72, 0x4038aa3b, v72
	v_mul_f32_e32 v73, 0x4038aa3b, v73
	v_exp_f32_e32 v72, v72
	v_exp_f32_e32 v73, v73
	v_pk_mul_f32 v[74:75], v[74:75], 0.5 op_sel_hi:[1,0]
	v_lshl_add_u64 v[78:79], v[82:83], 0, v[122:123]
	v_add_f32_e32 v72, 1.0, v72
	v_add_f32_e32 v73, 1.0, v73
	v_rcp_f32_e32 v72, v72
	v_rcp_f32_e32 v73, v73
	s_nop 0
	v_pk_fma_f32 v[72:73], v[72:73], 2.0, 1.0 op_sel_hi:[1,0,0] neg_lo:[1,0,0] neg_hi:[1,0,0]
	s_nop 0
	v_pk_add_f32 v[72:73], v[72:73], 1.0 op_sel_hi:[1,0]
	s_nop 0
	v_pk_mul_f32 v[72:73], v[74:75], v[72:73]
	v_mul_f32_e32 v74, 0x3d372713, v71
	v_mul_f32_e32 v74, v71, v74
	v_fma_f32 v74, v71, v74, v71
	v_mul_f32_e32 v74, 0x3f4c422a, v74
	v_mul_f32_e32 v74, 0x4038aa3b, v74
	v_exp_f32_e32 v74, v74
	v_pk_mul_f32 v[70:71], v[70:71], 0.5 op_sel_hi:[1,0]
	v_add_f32_e32 v74, 1.0, v74
	v_rcp_f32_e32 v77, v74
	s_nop 0
	v_pk_fma_f32 v[74:75], v[76:77], 2.0, 1.0 op_sel_hi:[1,0,0] neg_lo:[1,0,0] neg_hi:[1,0,0]
	s_nop 0
	v_pk_add_f32 v[74:75], v[74:75], 1.0 op_sel_hi:[1,0]
	s_nop 0
	v_pk_mul_f32 v[70:71], v[70:71], v[74:75]
	v_mul_f32_e32 v75, 0x3d372713, v68
	v_mul_f32_e32 v75, v68, v75
	v_fma_f32 v75, v68, v75, v68
	v_mul_f32_e32 v75, 0x3f4c422a, v75
	v_mul_f32_e32 v75, 0x4038aa3b, v75
	v_exp_f32_e32 v75, v75
	v_mul_f32_e32 v74, 0x3d372713, v66
	v_mul_f32_e32 v74, v66, v74
	v_fma_f32 v74, v66, v74, v66
	v_add_f32_e32 v75, 1.0, v75
	v_rcp_f32_e32 v76, v75
	v_mul_f32_e32 v75, 0x3d372713, v67
	v_mul_f32_e32 v75, v67, v75
	v_fma_f32 v75, v67, v75, v67
	v_mul_f32_e32 v74, 0x3f4c422a, v74
	v_mul_f32_e32 v75, 0x3f4c422a, v75
	v_mul_f32_e32 v74, 0x4038aa3b, v74
	v_mul_f32_e32 v75, 0x4038aa3b, v75
	v_exp_f32_e32 v74, v74
	v_exp_f32_e32 v75, v75
	v_pk_mul_f32 v[66:67], v[66:67], 0.5 op_sel_hi:[1,0]
	v_add_f32_e32 v74, 1.0, v74
	v_add_f32_e32 v75, 1.0, v75
	v_rcp_f32_e32 v74, v74
	v_rcp_f32_e32 v75, v75
	s_nop 0
	v_pk_fma_f32 v[74:75], v[74:75], 2.0, 1.0 op_sel_hi:[1,0,0] neg_lo:[1,0,0] neg_hi:[1,0,0]
	s_nop 0
	v_pk_add_f32 v[74:75], v[74:75], 1.0 op_sel_hi:[1,0]
	s_nop 0
	v_pk_mul_f32 v[74:75], v[66:67], v[74:75]
	v_mul_f32_e32 v66, 0x3d372713, v69
	v_mul_f32_e32 v66, v69, v66
	v_fma_f32 v66, v69, v66, v69
	v_mul_f32_e32 v66, 0x3f4c422a, v66
	v_mul_f32_e32 v66, 0x4038aa3b, v66
	v_exp_f32_e32 v66, v66
	v_pk_mul_f32 v[68:69], v[68:69], 0.5 op_sel_hi:[1,0]
	v_add_f32_e32 v66, 1.0, v66
	v_rcp_f32_e32 v77, v66
	s_nop 0
	v_pk_fma_f32 v[66:67], v[76:77], 2.0, 1.0 op_sel_hi:[1,0,0] neg_lo:[1,0,0] neg_hi:[1,0,0]
	s_nop 0
	v_pk_add_f32 v[66:67], v[66:67], 1.0 op_sel_hi:[1,0]
	s_nop 0
	v_pk_mul_f32 v[76:77], v[68:69], v[66:67]
	v_cvt_pk_bf16_f32 v68, v70, v71
	v_lshlrev_b64 v[70:71], 10, v[78:79]
	v_lshl_add_u64 v[70:71], s[16:17], 0, v[70:71]
	v_lshl_add_u64 v[70:71], v[70:71], 0, s[46:47]
	v_cvt_pk_bf16_f32 v66, v72, v73
	v_cvt_pk_bf16_f32 v67, v74, v75
	v_cvt_pk_bf16_f32 v69, v76, v77
	v_lshl_add_u64 v[70:71], v[70:71], 0, v[138:139]
	global_store_dwordx4 v[70:71], v[66:69], off
	s_nop 1
	v_add_u32_e32 v66, 0x80, v142
	v_ashrrev_i32_e32 v67, 31, v66
	v_lshlrev_b64 v[66:67], 5, v[66:67]
	v_lshl_add_u64 v[68:69], v[66:67], 0, s[60:61]
	v_lshl_add_u64 v[70:71], v[68:69], 0, v[140:141]
	v_lshlrev_b64 v[74:75], 5, v[70:71]
	v_or_b32_e32 v74, v74, v138
	v_lshl_add_u64 v[70:71], s[12:13], 0, v[74:75]
	global_load_dwordx4 v[182:185], v218, s[78:79]
	s_waitcnt vmcnt(5)
	v_lshlrev_b32_e32 v76, 16, v198
	v_and_b32_e32 v77, 0xffff0000, v198
	v_lshlrev_b32_e32 v70, 16, v199
	v_and_b32_e32 v71, 0xffff0000, v199
	v_pk_add_f32 v[76:77], v[58:59], v[76:77]
	v_lshl_add_u64 v[58:59], s[14:15], 0, v[74:75]
	v_pk_add_f32 v[80:81], v[60:61], v[70:71]
	global_load_dwordx4 v[186:189], v219, s[78:79]
	s_waitcnt vmcnt(5)
	v_lshlrev_b32_e32 v78, 16, v200
	v_and_b32_e32 v79, 0xffff0000, v200
	v_lshlrev_b32_e32 v72, 16, v201
	v_and_b32_e32 v73, 0xffff0000, v201
	v_pk_add_f32 v[78:79], v[62:63], v[78:79]
	v_pk_add_f32 v[82:83], v[64:65], v[72:73]
	global_load_dwordx4 v[190:193], v143, s[44:45] offset:16
	s_waitcnt vmcnt(5)
	global_load_dwordx4 v[194:197], v143, s[44:45]
	s_waitcnt vmcnt(5)
	v_lshlrev_b32_e32 v84, 16, v172
	v_and_b32_e32 v85, 0xffff0000, v172
	v_lshlrev_b32_e32 v60, 16, v173
	v_and_b32_e32 v61, 0xffff0000, v173
	v_lshlrev_b32_e32 v74, 16, v170
	v_and_b32_e32 v75, 0xffff0000, v170
	v_pk_fma_f32 v[62:63], v[174:175], v[84:85], v[78:79]
	v_pk_fma_f32 v[60:61], v[176:177], v[60:61], v[82:83]
	v_mul_f32_e32 v65, 0x3d372713, v62
	v_mul_f32_e32 v65, v62, v65
	v_fma_f32 v65, v62, v65, v62
	v_mul_f32_e32 v65, 0x3f4c422a, v65
	v_mul_f32_e32 v65, 0x4038aa3b, v65
	v_exp_f32_e32 v65, v65
	v_lshlrev_b32_e32 v58, 16, v171
	v_and_b32_e32 v59, 0xffff0000, v171
	v_pk_fma_f32 v[70:71], v[178:179], v[74:75], v[76:77]
	v_add_f32_e32 v65, 1.0, v65
	v_pk_fma_f32 v[58:59], v[180:181], v[58:59], v[80:81]
	v_mul_f32_e32 v64, 0x3d372713, v70
	v_rcp_f32_e32 v72, v65
	v_mul_f32_e32 v65, 0x3d372713, v71
	v_mul_f32_e32 v64, v70, v64
	v_mul_f32_e32 v65, v71, v65
	v_fma_f32 v64, v70, v64, v70
	v_fma_f32 v65, v71, v65, v71
	v_mul_f32_e32 v64, 0x3f4c422a, v64
	v_mul_f32_e32 v65, 0x3f4c422a, v65
	v_mul_f32_e32 v64, 0x4038aa3b, v64
	v_mul_f32_e32 v65, 0x4038aa3b, v65
	v_exp_f32_e32 v64, v64
	v_exp_f32_e32 v65, v65
	v_pk_mul_f32 v[70:71], v[70:71], 0.5 op_sel_hi:[1,0]
	v_lshl_add_u64 v[74:75], v[66:67], 0, v[140:141]
	v_add_f32_e32 v64, 1.0, v64
	v_add_f32_e32 v65, 1.0, v65
	v_rcp_f32_e32 v64, v64
	v_rcp_f32_e32 v65, v65
	s_nop 0
	v_pk_fma_f32 v[64:65], v[64:65], 2.0, 1.0 op_sel_hi:[1,0,0] neg_lo:[1,0,0] neg_hi:[1,0,0]
	s_nop 0
	v_pk_add_f32 v[64:65], v[64:65], 1.0 op_sel_hi:[1,0]
	s_nop 0
	v_pk_mul_f32 v[64:65], v[70:71], v[64:65]
	v_mul_f32_e32 v70, 0x3d372713, v63
	v_mul_f32_e32 v70, v63, v70
	v_fma_f32 v70, v63, v70, v63
	v_mul_f32_e32 v70, 0x3f4c422a, v70
	v_mul_f32_e32 v70, 0x4038aa3b, v70
	v_exp_f32_e32 v70, v70
	v_pk_mul_f32 v[62:63], v[62:63], 0.5 op_sel_hi:[1,0]
	v_add_f32_e32 v70, 1.0, v70
	v_rcp_f32_e32 v73, v70
	s_nop 0
	v_pk_fma_f32 v[70:71], v[72:73], 2.0, 1.0 op_sel_hi:[1,0,0] neg_lo:[1,0,0] neg_hi:[1,0,0]
	s_nop 0
	v_pk_add_f32 v[70:71], v[70:71], 1.0 op_sel_hi:[1,0]
	s_nop 0
	v_pk_mul_f32 v[62:63], v[62:63], v[70:71]
	v_mul_f32_e32 v71, 0x3d372713, v60
	v_mul_f32_e32 v71, v60, v71
	v_fma_f32 v71, v60, v71, v60
	v_mul_f32_e32 v71, 0x3f4c422a, v71
	v_mul_f32_e32 v71, 0x4038aa3b, v71
	v_exp_f32_e32 v71, v71
	v_mul_f32_e32 v70, 0x3d372713, v58
	v_mul_f32_e32 v70, v58, v70
	v_fma_f32 v70, v58, v70, v58
	v_add_f32_e32 v71, 1.0, v71
	v_rcp_f32_e32 v72, v71
	v_mul_f32_e32 v71, 0x3d372713, v59
	v_mul_f32_e32 v71, v59, v71
	v_fma_f32 v71, v59, v71, v59
	v_mul_f32_e32 v70, 0x3f4c422a, v70
	v_mul_f32_e32 v71, 0x3f4c422a, v71
	v_mul_f32_e32 v70, 0x4038aa3b, v70
	v_mul_f32_e32 v71, 0x4038aa3b, v71
	v_exp_f32_e32 v70, v70
	v_exp_f32_e32 v71, v71
	v_pk_mul_f32 v[58:59], v[58:59], 0.5 op_sel_hi:[1,0]
	v_add_f32_e32 v70, 1.0, v70
	v_add_f32_e32 v71, 1.0, v71
	v_rcp_f32_e32 v70, v70
	v_rcp_f32_e32 v71, v71
	s_nop 0
	v_pk_fma_f32 v[70:71], v[70:71], 2.0, 1.0 op_sel_hi:[1,0,0] neg_lo:[1,0,0] neg_hi:[1,0,0]
	s_nop 0
	v_pk_add_f32 v[70:71], v[70:71], 1.0 op_sel_hi:[1,0]
	s_nop 0
	v_pk_mul_f32 v[70:71], v[58:59], v[70:71]
	v_mul_f32_e32 v58, 0x3d372713, v61
	v_mul_f32_e32 v58, v61, v58
	v_fma_f32 v58, v61, v58, v61
	v_mul_f32_e32 v58, 0x3f4c422a, v58
	v_mul_f32_e32 v58, 0x4038aa3b, v58
	v_exp_f32_e32 v58, v58
	v_pk_mul_f32 v[60:61], v[60:61], 0.5 op_sel_hi:[1,0]
	v_add_f32_e32 v58, 1.0, v58
	v_rcp_f32_e32 v73, v58
	s_nop 0
	v_pk_fma_f32 v[58:59], v[72:73], 2.0, 1.0 op_sel_hi:[1,0,0] neg_lo:[1,0,0] neg_hi:[1,0,0]
	s_nop 0
	v_pk_add_f32 v[58:59], v[58:59], 1.0 op_sel_hi:[1,0]
	s_nop 0
	v_pk_mul_f32 v[72:73], v[60:61], v[58:59]
	v_cvt_pk_bf16_f32 v60, v62, v63
	v_lshlrev_b64 v[62:63], 10, v[74:75]
	v_lshl_add_u64 v[62:63], s[16:17], 0, v[62:63]
	v_lshl_add_u64 v[62:63], v[62:63], 0, s[46:47]
	v_cvt_pk_bf16_f32 v58, v64, v65
	v_cvt_pk_bf16_f32 v59, v70, v71
	v_cvt_pk_bf16_f32 v61, v72, v73
	v_lshl_add_u64 v[62:63], v[62:63], 0, v[138:139]
	global_store_dwordx4 v[62:63], v[58:61], off
	s_nop 1
	v_lshl_add_u64 v[58:59], v[68:69], 0, v[122:123]
	v_lshlrev_b64 v[62:63], 5, v[58:59]
	v_or_b32_e32 v62, v62, v138
	v_lshl_add_u64 v[58:59], s[12:13], 0, v[62:63]
	global_load_dwordx4 v[198:201], v143, s[44:45] offset:16
	s_waitcnt vmcnt(5)
	v_lshlrev_b32_e32 v64, 16, v182
	v_and_b32_e32 v65, 0xffff0000, v182
	v_lshlrev_b32_e32 v58, 16, v183
	v_and_b32_e32 v59, 0xffff0000, v183
	v_pk_add_f32 v[64:65], v[50:51], v[64:65]
	v_lshl_add_u64 v[50:51], s[14:15], 0, v[62:63]
	v_lshlrev_b32_e32 v68, 16, v184
	v_and_b32_e32 v69, 0xffff0000, v184
	v_lshlrev_b32_e32 v60, 16, v185
	v_and_b32_e32 v61, 0xffff0000, v185
	v_pk_add_f32 v[70:71], v[52:53], v[58:59]
	global_load_dwordx4 v[170:173], v143, s[44:45]
	s_waitcnt vmcnt(5)
	v_pk_add_f32 v[68:69], v[54:55], v[68:69]
	v_pk_add_f32 v[72:73], v[56:57], v[60:61]
	global_load_dwordx4 v[174:177], v220, s[78:79]
	s_waitcnt vmcnt(5)
	global_load_dwordx4 v[178:181], v221, s[78:79]
	s_waitcnt vmcnt(5)
	v_lshlrev_b32_e32 v62, 16, v186
	v_and_b32_e32 v63, 0xffff0000, v186
	v_lshlrev_b32_e32 v74, 16, v188
	v_and_b32_e32 v75, 0xffff0000, v188
	v_lshlrev_b32_e32 v52, 16, v189
	v_and_b32_e32 v53, 0xffff0000, v189
	v_pk_fma_f32 v[58:59], v[194:195], v[62:63], v[64:65]
	v_pk_fma_f32 v[52:53], v[192:193], v[52:53], v[72:73]
	v_mul_f32_e32 v56, 0x3d372713, v58
	v_mul_f32_e32 v56, v58, v56
	v_fma_f32 v56, v58, v56, v58
	v_mul_f32_e32 v56, 0x3f4c422a, v56
	v_mul_f32_e32 v56, 0x4038aa3b, v56
	v_exp_f32_e32 v56, v56
	v_pk_fma_f32 v[54:55], v[190:191], v[74:75], v[68:69]
	v_mul_f32_e32 v57, 0.5, v58
	v_mul_f32_e32 v58, 0.5, v59
	v_add_f32_e32 v56, 1.0, v56
	v_rcp_f32_e32 v56, v56
	v_lshlrev_b32_e32 v50, 16, v187
	v_and_b32_e32 v51, 0xffff0000, v187
	v_pk_fma_f32 v[50:51], v[196:197], v[50:51], v[70:71]
	v_fma_f32 v56, v56, -2.0, 1.0
	v_add_f32_e32 v56, 1.0, v56
	v_mul_f32_e32 v56, v57, v56
	v_mul_f32_e32 v57, 0x3d372713, v54
	v_mul_f32_e32 v57, v54, v57
	v_fma_f32 v57, v54, v57, v54
	v_mul_f32_e32 v57, 0x3f4c422a, v57
	v_mul_f32_e32 v57, 0x4038aa3b, v57
	v_exp_f32_e32 v57, v57
	v_mul_f32_e32 v54, 0.5, v54
	v_add_f32_e32 v57, 1.0, v57
	v_rcp_f32_e32 v57, v57
	s_nop 0
	v_fma_f32 v57, v57, -2.0, 1.0
	v_add_f32_e32 v57, 1.0, v57
	v_mul_f32_e32 v57, v54, v57
	v_mul_f32_e32 v54, 0x3d372713, v59
	v_mul_f32_e32 v54, v59, v54
	v_fma_f32 v54, v59, v54, v59
	v_mul_f32_e32 v54, 0x3f4c422a, v54
	v_mul_f32_e32 v54, 0x4038aa3b, v54
	v_exp_f32_e32 v54, v54
	s_nop 0
	v_add_f32_e32 v54, 1.0, v54
	v_rcp_f32_e32 v54, v54
	s_nop 0
	v_fma_f32 v54, v54, -2.0, 1.0
	v_add_f32_e32 v54, 1.0, v54
	v_mul_f32_e32 v58, v58, v54
	v_mul_f32_e32 v54, 0x3d372713, v55
	v_mul_f32_e32 v54, v55, v54
	v_fma_f32 v54, v55, v54, v55
	v_mul_f32_e32 v54, 0x3f4c422a, v54
	v_mul_f32_e32 v54, 0x4038aa3b, v54
	v_exp_f32_e32 v54, v54
	v_mul_f32_e32 v55, 0.5, v55
	v_add_f32_e32 v54, 1.0, v54
	v_rcp_f32_e32 v54, v54
	s_nop 0
	v_fma_f32 v54, v54, -2.0, 1.0
	v_add_f32_e32 v54, 1.0, v54
	v_mul_f32_e32 v59, v55, v54
	v_mul_f32_e32 v54, 0x3d372713, v50
	v_mul_f32_e32 v54, v50, v54
	v_fma_f32 v54, v50, v54, v50
	v_mul_f32_e32 v54, 0x3f4c422a, v54
	v_mul_f32_e32 v54, 0x4038aa3b, v54
	v_exp_f32_e32 v54, v54
	v_mul_f32_e32 v50, 0.5, v50
	v_add_f32_e32 v54, 1.0, v54
	v_rcp_f32_e32 v54, v54
	s_nop 0
	v_fma_f32 v54, v54, -2.0, 1.0
	v_add_f32_e32 v54, 1.0, v54
	v_mul_f32_e32 v60, v50, v54
	v_mul_f32_e32 v50, 0x3d372713, v52
	v_mul_f32_e32 v50, v52, v50
	v_fma_f32 v50, v52, v50, v52
	v_mul_f32_e32 v50, 0x3f4c422a, v50
	v_mul_f32_e32 v50, 0x4038aa3b, v50
	v_exp_f32_e32 v50, v50
	v_mul_f32_e32 v52, 0.5, v52
	v_lshl_add_u64 v[54:55], v[66:67], 0, v[122:123]
	v_lshlrev_b64 v[54:55], 10, v[54:55]
	v_add_f32_e32 v50, 1.0, v50
	v_rcp_f32_e32 v50, v50
	v_lshl_add_u64 v[54:55], s[16:17], 0, v[54:55]
	v_lshl_add_u64 v[54:55], v[54:55], 0, s[46:47]
	v_lshl_add_u64 v[54:55], v[54:55], 0, v[138:139]
	v_fma_f32 v50, v50, -2.0, 1.0
	v_add_f32_e32 v50, 1.0, v50
	v_mul_f32_e32 v61, v52, v50
	v_mul_f32_e32 v50, 0x3d372713, v51
	v_mul_f32_e32 v50, v51, v50
	v_fma_f32 v50, v51, v50, v51
	v_mul_f32_e32 v50, 0x3f4c422a, v50
	v_mul_f32_e32 v50, 0x4038aa3b, v50
	v_exp_f32_e32 v50, v50
	v_mul_f32_e32 v51, 0.5, v51
	v_mul_f32_e32 v52, 0.5, v53
	v_add_f32_e32 v50, 1.0, v50
	v_rcp_f32_e32 v50, v50
	s_nop 0
	v_fma_f32 v50, v50, -2.0, 1.0
	v_add_f32_e32 v50, 1.0, v50
	v_mul_f32_e32 v51, v51, v50
	v_mul_f32_e32 v50, 0x3d372713, v53
	v_mul_f32_e32 v50, v53, v50
	v_fma_f32 v50, v53, v50, v53
	v_mul_f32_e32 v50, 0x3f4c422a, v50
	v_mul_f32_e32 v50, 0x4038aa3b, v50
	v_exp_f32_e32 v50, v50
	v_cvt_pk_bf16_f32 v51, v60, v51
	v_add_f32_e32 v50, 1.0, v50
	v_rcp_f32_e32 v50, v50
	s_nop 0
	v_fma_f32 v50, v50, -2.0, 1.0
	v_add_f32_e32 v50, 1.0, v50
	v_mul_f32_e32 v53, v52, v50
	v_cvt_pk_bf16_f32 v50, v56, v58
	v_cvt_pk_bf16_f32 v52, v57, v59
	v_cvt_pk_bf16_f32 v53, v61, v53
	global_store_dwordx4 v[54:55], v[50:53], off
	global_load_dwordx4 v[182:185], v222, s[78:79]
	s_waitcnt vmcnt(5)
	s_nop 0
	global_load_dwordx4 v[186:189], v223, s[78:79]
	s_waitcnt vmcnt(5)
	v_add_u32_e32 v50, 0x90, v142
	v_ashrrev_i32_e32 v51, 31, v50
	v_lshlrev_b64 v[50:51], 5, v[50:51]
	v_lshl_add_u64 v[52:53], v[50:51], 0, s[60:61]
	v_lshl_add_u64 v[62:63], v[52:53], 0, v[140:141]
	v_lshlrev_b64 v[66:67], 5, v[62:63]
	v_or_b32_e32 v66, v66, v138
	v_lshl_add_u64 v[62:63], s[12:13], 0, v[66:67]
	global_load_dwordx4 v[190:193], v143, s[44:45] offset:16
	s_waitcnt vmcnt(5)
	v_lshlrev_b32_e32 v68, 16, v174
	v_and_b32_e32 v69, 0xffff0000, v174
	v_lshlrev_b32_e32 v62, 16, v175
	v_and_b32_e32 v63, 0xffff0000, v175
	v_pk_add_f32 v[68:69], v[42:43], v[68:69]
	v_lshl_add_u64 v[42:43], s[14:15], 0, v[66:67]
	v_pk_add_f32 v[62:63], v[44:45], v[62:63]
	global_load_dwordx4 v[194:197], v143, s[44:45]
	s_waitcnt vmcnt(5)
	v_lshlrev_b32_e32 v70, 16, v176
	v_and_b32_e32 v71, 0xffff0000, v176
	v_lshlrev_b32_e32 v64, 16, v177
	v_and_b32_e32 v65, 0xffff0000, v177
	v_pk_add_f32 v[48:49], v[48:49], v[64:65]
	v_pk_add_f32 v[46:47], v[46:47], v[70:71]
	v_lshlrev_b32_e32 v64, 16, v178
	v_and_b32_e32 v65, 0xffff0000, v178
	v_lshlrev_b32_e32 v42, 16, v179
	v_and_b32_e32 v43, 0xffff0000, v179
	v_lshlrev_b32_e32 v70, 16, v181
	v_and_b32_e32 v71, 0xffff0000, v181
	v_pk_fma_f32 v[58:59], v[170:171], v[64:65], v[68:69]
	v_lshlrev_b32_e32 v66, 16, v180
	v_and_b32_e32 v67, 0xffff0000, v180
	v_pk_fma_f32 v[44:45], v[172:173], v[42:43], v[62:63]
	v_pk_fma_f32 v[42:43], v[200:201], v[70:71], v[48:49]
	v_mul_f32_e32 v48, 0x3d372713, v58
	v_mul_f32_e32 v48, v58, v48
	v_fma_f32 v48, v58, v48, v58
	v_mul_f32_e32 v48, 0x3f4c422a, v48
	v_mul_f32_e32 v48, 0x4038aa3b, v48
	v_exp_f32_e32 v48, v48
	v_pk_fma_f32 v[46:47], v[198:199], v[66:67], v[46:47]
	v_mul_f32_e32 v49, 0.5, v58
	v_mul_f32_e32 v54, 0.5, v59
	v_add_f32_e32 v48, 1.0, v48
	v_rcp_f32_e32 v48, v48
	s_nop 0
	v_fma_f32 v48, v48, -2.0, 1.0
	v_add_f32_e32 v48, 1.0, v48
	v_mul_f32_e32 v48, v49, v48
	v_mul_f32_e32 v49, 0x3d372713, v46
	v_mul_f32_e32 v49, v46, v49
	v_fma_f32 v49, v46, v49, v46
	v_mul_f32_e32 v49, 0x3f4c422a, v49
	v_mul_f32_e32 v49, 0x4038aa3b, v49
	v_exp_f32_e32 v49, v49
	v_mul_f32_e32 v46, 0.5, v46
	v_add_f32_e32 v49, 1.0, v49
	v_rcp_f32_e32 v49, v49
	s_nop 0
	v_fma_f32 v49, v49, -2.0, 1.0
	v_add_f32_e32 v49, 1.0, v49
	v_mul_f32_e32 v49, v46, v49
	v_mul_f32_e32 v46, 0x3d372713, v59
	v_mul_f32_e32 v46, v59, v46
	v_fma_f32 v46, v59, v46, v59
	v_mul_f32_e32 v46, 0x3f4c422a, v46
	v_mul_f32_e32 v46, 0x4038aa3b, v46
	v_exp_f32_e32 v46, v46
	s_nop 0
	v_add_f32_e32 v46, 1.0, v46
	v_rcp_f32_e32 v46, v46
	s_nop 0
	v_fma_f32 v46, v46, -2.0, 1.0
	v_add_f32_e32 v46, 1.0, v46
	v_mul_f32_e32 v54, v54, v46
	v_mul_f32_e32 v46, 0x3d372713, v47
	v_mul_f32_e32 v46, v47, v46
	v_fma_f32 v46, v47, v46, v47
	v_mul_f32_e32 v46, 0x3f4c422a, v46
	v_mul_f32_e32 v46, 0x4038aa3b, v46
	v_exp_f32_e32 v46, v46
	v_mul_f32_e32 v47, 0.5, v47
	v_add_f32_e32 v46, 1.0, v46
	v_rcp_f32_e32 v46, v46
	s_nop 0
	v_fma_f32 v46, v46, -2.0, 1.0
	v_add_f32_e32 v46, 1.0, v46
	v_mul_f32_e32 v55, v47, v46
	v_mul_f32_e32 v46, 0x3d372713, v44
	v_mul_f32_e32 v46, v44, v46
	v_fma_f32 v46, v44, v46, v44
	v_mul_f32_e32 v46, 0x3f4c422a, v46
	v_mul_f32_e32 v46, 0x4038aa3b, v46
	v_exp_f32_e32 v46, v46
	v_mul_f32_e32 v44, 0.5, v44
	v_add_f32_e32 v46, 1.0, v46
	v_rcp_f32_e32 v46, v46
	s_nop 0
	v_fma_f32 v46, v46, -2.0, 1.0
	v_add_f32_e32 v46, 1.0, v46
	v_mul_f32_e32 v44, v44, v46
	v_mul_f32_e32 v46, 0x3d372713, v42
	v_mul_f32_e32 v46, v42, v46
	v_fma_f32 v46, v42, v46, v42
	v_mul_f32_e32 v46, 0x3f4c422a, v46
	v_mul_f32_e32 v46, 0x4038aa3b, v46
	v_exp_f32_e32 v46, v46
	v_mul_f32_e32 v42, 0.5, v42
	v_add_f32_e32 v46, 1.0, v46
	v_rcp_f32_e32 v46, v46
	s_nop 0
	v_fma_f32 v46, v46, -2.0, 1.0
	v_add_f32_e32 v46, 1.0, v46
	v_mul_f32_e32 v56, v42, v46
	v_mul_f32_e32 v42, 0x3d372713, v45
	v_mul_f32_e32 v42, v45, v42
	v_fma_f32 v42, v45, v42, v45
	v_mul_f32_e32 v42, 0x3f4c422a, v42
	v_mul_f32_e32 v42, 0x4038aa3b, v42
	v_exp_f32_e32 v42, v42
	v_mul_f32_e32 v45, 0.5, v45
	v_lshl_add_u64 v[46:47], v[50:51], 0, v[140:141]
	v_lshlrev_b64 v[46:47], 10, v[46:47]
	v_add_f32_e32 v42, 1.0, v42
	v_rcp_f32_e32 v42, v42
	v_lshl_add_u64 v[46:47], s[16:17], 0, v[46:47]
	v_lshl_add_u64 v[46:47], v[46:47], 0, s[46:47]
	v_lshl_add_u64 v[46:47], v[46:47], 0, v[138:139]
	v_fma_f32 v42, v42, -2.0, 1.0
	v_add_f32_e32 v42, 1.0, v42
	v_mul_f32_e32 v45, v45, v42
	v_mul_f32_e32 v42, 0x3d372713, v43
	v_mul_f32_e32 v42, v43, v42
	v_fma_f32 v42, v43, v42, v43
	v_mul_f32_e32 v42, 0x3f4c422a, v42
	v_mul_f32_e32 v42, 0x4038aa3b, v42
	v_exp_f32_e32 v42, v42
	v_mul_f32_e32 v43, 0.5, v43
	v_add_f32_e32 v42, 1.0, v42
	v_rcp_f32_e32 v42, v42
	s_nop 0
	v_fma_f32 v42, v42, -2.0, 1.0
	v_add_f32_e32 v42, 1.0, v42
	v_mul_f32_e32 v57, v43, v42
	v_cvt_pk_bf16_f32 v42, v48, v54
	v_cvt_pk_bf16_f32 v43, v44, v45
	v_cvt_pk_bf16_f32 v44, v49, v55
	v_cvt_pk_bf16_f32 v45, v56, v57
	global_store_dwordx4 v[46:47], v[42:45], off
	s_nop 1
	v_lshl_add_u64 v[42:43], v[52:53], 0, v[122:123]
	v_lshlrev_b64 v[46:47], 5, v[42:43]
	v_or_b32_e32 v46, v46, v138
	v_lshl_add_u64 v[42:43], s[12:13], 0, v[46:47]
	global_load_dwordx4 v[198:201], v143, s[44:45] offset:16
	s_waitcnt vmcnt(5)
	v_lshlrev_b32_e32 v48, 16, v182
	v_and_b32_e32 v49, 0xffff0000, v182
	v_lshlrev_b32_e32 v42, 16, v183
	v_and_b32_e32 v43, 0xffff0000, v183
	v_pk_add_f32 v[48:49], v[34:35], v[48:49]
	v_lshl_add_u64 v[34:35], s[14:15], 0, v[46:47]
	v_lshlrev_b32_e32 v52, 16, v184
	v_and_b32_e32 v53, 0xffff0000, v184
	v_lshlrev_b32_e32 v44, 16, v185
	v_and_b32_e32 v45, 0xffff0000, v185
	v_pk_add_f32 v[54:55], v[36:37], v[42:43]
	global_load_dwordx4 v[170:173], v143, s[44:45]
	s_waitcnt vmcnt(5)
	v_pk_add_f32 v[52:53], v[38:39], v[52:53]
	v_pk_add_f32 v[56:57], v[40:41], v[44:45]
	global_load_dwordx4 v[174:177], v224, s[78:79]
	s_waitcnt vmcnt(5)
	global_load_dwordx4 v[178:181], v226, s[78:79]
	s_waitcnt vmcnt(5)
	v_lshlrev_b32_e32 v46, 16, v186
	v_and_b32_e32 v47, 0xffff0000, v186
	v_lshlrev_b32_e32 v58, 16, v188
	v_and_b32_e32 v59, 0xffff0000, v188
	v_lshlrev_b32_e32 v36, 16, v189
	v_and_b32_e32 v37, 0xffff0000, v189
	v_pk_fma_f32 v[42:43], v[194:195], v[46:47], v[48:49]
	v_pk_fma_f32 v[36:37], v[192:193], v[36:37], v[56:57]
	v_mul_f32_e32 v40, 0x3d372713, v42
	v_mul_f32_e32 v40, v42, v40
	v_fma_f32 v40, v42, v40, v42
	v_mul_f32_e32 v40, 0x3f4c422a, v40
	v_mul_f32_e32 v40, 0x4038aa3b, v40
	v_exp_f32_e32 v40, v40
	v_pk_fma_f32 v[38:39], v[190:191], v[58:59], v[52:53]
	v_mul_f32_e32 v41, 0.5, v42
	v_mul_f32_e32 v42, 0.5, v43
	v_add_f32_e32 v40, 1.0, v40
	v_rcp_f32_e32 v40, v40
	v_lshlrev_b32_e32 v34, 16, v187
	v_and_b32_e32 v35, 0xffff0000, v187
	v_pk_fma_f32 v[34:35], v[196:197], v[34:35], v[54:55]
	v_fma_f32 v40, v40, -2.0, 1.0
	v_add_f32_e32 v40, 1.0, v40
	v_mul_f32_e32 v40, v41, v40
	v_mul_f32_e32 v41, 0x3d372713, v38
	v_mul_f32_e32 v41, v38, v41
	v_fma_f32 v41, v38, v41, v38
	v_mul_f32_e32 v41, 0x3f4c422a, v41
	v_mul_f32_e32 v41, 0x4038aa3b, v41
	v_exp_f32_e32 v41, v41
	v_mul_f32_e32 v38, 0.5, v38
	v_add_f32_e32 v41, 1.0, v41
	v_rcp_f32_e32 v41, v41
	s_nop 0
	v_fma_f32 v41, v41, -2.0, 1.0
	v_add_f32_e32 v41, 1.0, v41
	v_mul_f32_e32 v41, v38, v41
	v_mul_f32_e32 v38, 0x3d372713, v43
	v_mul_f32_e32 v38, v43, v38
	v_fma_f32 v38, v43, v38, v43
	v_mul_f32_e32 v38, 0x3f4c422a, v38
	v_mul_f32_e32 v38, 0x4038aa3b, v38
	v_exp_f32_e32 v38, v38
	s_nop 0
	v_add_f32_e32 v38, 1.0, v38
	v_rcp_f32_e32 v38, v38
	s_nop 0
	v_fma_f32 v38, v38, -2.0, 1.0
	v_add_f32_e32 v38, 1.0, v38
	v_mul_f32_e32 v42, v42, v38
	v_mul_f32_e32 v38, 0x3d372713, v39
	v_mul_f32_e32 v38, v39, v38
	v_fma_f32 v38, v39, v38, v39
	v_mul_f32_e32 v38, 0x3f4c422a, v38
	v_mul_f32_e32 v38, 0x4038aa3b, v38
	v_exp_f32_e32 v38, v38
	v_mul_f32_e32 v39, 0.5, v39
	v_add_f32_e32 v38, 1.0, v38
	v_rcp_f32_e32 v38, v38
	s_nop 0
	v_fma_f32 v38, v38, -2.0, 1.0
	v_add_f32_e32 v38, 1.0, v38
	v_mul_f32_e32 v43, v39, v38
	v_mul_f32_e32 v38, 0x3d372713, v34
	v_mul_f32_e32 v38, v34, v38
	v_fma_f32 v38, v34, v38, v34
	v_mul_f32_e32 v38, 0x3f4c422a, v38
	v_mul_f32_e32 v38, 0x4038aa3b, v38
	v_exp_f32_e32 v38, v38
	v_mul_f32_e32 v34, 0.5, v34
	v_add_f32_e32 v38, 1.0, v38
	v_rcp_f32_e32 v38, v38
	s_nop 0
	v_fma_f32 v38, v38, -2.0, 1.0
	v_add_f32_e32 v38, 1.0, v38
	v_mul_f32_e32 v44, v34, v38
	v_mul_f32_e32 v34, 0x3d372713, v36
	v_mul_f32_e32 v34, v36, v34
	v_fma_f32 v34, v36, v34, v36
	v_mul_f32_e32 v34, 0x3f4c422a, v34
	v_mul_f32_e32 v34, 0x4038aa3b, v34
	v_exp_f32_e32 v34, v34
	v_mul_f32_e32 v36, 0.5, v36
	v_lshl_add_u64 v[38:39], v[50:51], 0, v[122:123]
	v_lshlrev_b64 v[38:39], 10, v[38:39]
	v_add_f32_e32 v34, 1.0, v34
	v_rcp_f32_e32 v34, v34
	v_lshl_add_u64 v[38:39], s[16:17], 0, v[38:39]
	v_lshl_add_u64 v[38:39], v[38:39], 0, s[46:47]
	v_lshl_add_u64 v[38:39], v[38:39], 0, v[138:139]
	v_fma_f32 v34, v34, -2.0, 1.0
	v_add_f32_e32 v34, 1.0, v34
	v_mul_f32_e32 v45, v36, v34
	v_mul_f32_e32 v34, 0x3d372713, v35
	v_mul_f32_e32 v34, v35, v34
	v_fma_f32 v34, v35, v34, v35
	v_mul_f32_e32 v34, 0x3f4c422a, v34
	v_mul_f32_e32 v34, 0x4038aa3b, v34
	v_exp_f32_e32 v34, v34
	v_mul_f32_e32 v35, 0.5, v35
	v_mul_f32_e32 v36, 0.5, v37
	v_add_f32_e32 v34, 1.0, v34
	v_rcp_f32_e32 v34, v34
	s_nop 0
	v_fma_f32 v34, v34, -2.0, 1.0
	v_add_f32_e32 v34, 1.0, v34
	v_mul_f32_e32 v35, v35, v34
	v_mul_f32_e32 v34, 0x3d372713, v37
	v_mul_f32_e32 v34, v37, v34
	v_fma_f32 v34, v37, v34, v37
	v_mul_f32_e32 v34, 0x3f4c422a, v34
	v_mul_f32_e32 v34, 0x4038aa3b, v34
	v_exp_f32_e32 v34, v34
	v_cvt_pk_bf16_f32 v35, v44, v35
	v_add_f32_e32 v34, 1.0, v34
	v_rcp_f32_e32 v34, v34
	s_nop 0
	v_fma_f32 v34, v34, -2.0, 1.0
	v_add_f32_e32 v34, 1.0, v34
	v_mul_f32_e32 v37, v36, v34
	v_cvt_pk_bf16_f32 v34, v40, v42
	v_cvt_pk_bf16_f32 v36, v41, v43
	v_cvt_pk_bf16_f32 v37, v45, v37
	global_store_dwordx4 v[38:39], v[34:37], off
	global_load_dwordx4 v[182:185], v227, s[78:79]
	s_waitcnt vmcnt(5)
	s_nop 0
	global_load_dwordx4 v[186:189], v228, s[78:79]
	s_waitcnt vmcnt(5)
	v_add_u32_e32 v34, 0xa0, v142
	v_ashrrev_i32_e32 v35, 31, v34
	v_lshlrev_b64 v[34:35], 5, v[34:35]
	v_lshl_add_u64 v[36:37], v[34:35], 0, s[60:61]
	v_lshl_add_u64 v[46:47], v[36:37], 0, v[140:141]
	v_lshlrev_b64 v[50:51], 5, v[46:47]
	v_or_b32_e32 v50, v50, v138
	v_lshl_add_u64 v[46:47], s[12:13], 0, v[50:51]
	global_load_dwordx4 v[190:193], v143, s[44:45] offset:16
	s_waitcnt vmcnt(5)
	v_lshlrev_b32_e32 v52, 16, v174
	v_and_b32_e32 v53, 0xffff0000, v174
	v_lshlrev_b32_e32 v46, 16, v175
	v_and_b32_e32 v47, 0xffff0000, v175
	v_pk_add_f32 v[52:53], v[26:27], v[52:53]
	v_lshl_add_u64 v[26:27], s[14:15], 0, v[50:51]
	v_pk_add_f32 v[46:47], v[28:29], v[46:47]
	global_load_dwordx4 v[194:197], v143, s[44:45]
	s_waitcnt vmcnt(5)
	v_lshlrev_b32_e32 v54, 16, v176
	v_and_b32_e32 v55, 0xffff0000, v176
	v_lshlrev_b32_e32 v48, 16, v177
	v_and_b32_e32 v49, 0xffff0000, v177
	v_pk_add_f32 v[32:33], v[32:33], v[48:49]
	v_pk_add_f32 v[30:31], v[30:31], v[54:55]
	v_lshlrev_b32_e32 v48, 16, v178
	v_and_b32_e32 v49, 0xffff0000, v178
	v_lshlrev_b32_e32 v26, 16, v179
	v_and_b32_e32 v27, 0xffff0000, v179
	v_lshlrev_b32_e32 v54, 16, v181
	v_and_b32_e32 v55, 0xffff0000, v181
	v_pk_fma_f32 v[42:43], v[170:171], v[48:49], v[52:53]
	v_lshlrev_b32_e32 v50, 16, v180
	v_and_b32_e32 v51, 0xffff0000, v180
	v_pk_fma_f32 v[28:29], v[172:173], v[26:27], v[46:47]
	v_pk_fma_f32 v[26:27], v[200:201], v[54:55], v[32:33]
	v_mul_f32_e32 v32, 0x3d372713, v42
	v_mul_f32_e32 v32, v42, v32
	v_fma_f32 v32, v42, v32, v42
	v_mul_f32_e32 v32, 0x3f4c422a, v32
	v_mul_f32_e32 v32, 0x4038aa3b, v32
	v_exp_f32_e32 v32, v32
	v_pk_fma_f32 v[30:31], v[198:199], v[50:51], v[30:31]
	v_mul_f32_e32 v33, 0.5, v42
	v_mul_f32_e32 v38, 0.5, v43
	v_add_f32_e32 v32, 1.0, v32
	v_rcp_f32_e32 v32, v32
	s_nop 0
	v_fma_f32 v32, v32, -2.0, 1.0
	v_add_f32_e32 v32, 1.0, v32
	v_mul_f32_e32 v32, v33, v32
	v_mul_f32_e32 v33, 0x3d372713, v30
	v_mul_f32_e32 v33, v30, v33
	v_fma_f32 v33, v30, v33, v30
	v_mul_f32_e32 v33, 0x3f4c422a, v33
	v_mul_f32_e32 v33, 0x4038aa3b, v33
	v_exp_f32_e32 v33, v33
	v_mul_f32_e32 v30, 0.5, v30
	v_add_f32_e32 v33, 1.0, v33
	v_rcp_f32_e32 v33, v33
	s_nop 0
	v_fma_f32 v33, v33, -2.0, 1.0
	v_add_f32_e32 v33, 1.0, v33
	v_mul_f32_e32 v33, v30, v33
	v_mul_f32_e32 v30, 0x3d372713, v43
	v_mul_f32_e32 v30, v43, v30
	v_fma_f32 v30, v43, v30, v43
	v_mul_f32_e32 v30, 0x3f4c422a, v30
	v_mul_f32_e32 v30, 0x4038aa3b, v30
	v_exp_f32_e32 v30, v30
	s_nop 0
	v_add_f32_e32 v30, 1.0, v30
	v_rcp_f32_e32 v30, v30
	s_nop 0
	v_fma_f32 v30, v30, -2.0, 1.0
	v_add_f32_e32 v30, 1.0, v30
	v_mul_f32_e32 v38, v38, v30
	v_mul_f32_e32 v30, 0x3d372713, v31
	v_mul_f32_e32 v30, v31, v30
	v_fma_f32 v30, v31, v30, v31
	v_mul_f32_e32 v30, 0x3f4c422a, v30
	v_mul_f32_e32 v30, 0x4038aa3b, v30
	v_exp_f32_e32 v30, v30
	v_mul_f32_e32 v31, 0.5, v31
	v_add_f32_e32 v30, 1.0, v30
	v_rcp_f32_e32 v30, v30
	s_nop 0
	v_fma_f32 v30, v30, -2.0, 1.0
	v_add_f32_e32 v30, 1.0, v30
	v_mul_f32_e32 v39, v31, v30
	v_mul_f32_e32 v30, 0x3d372713, v28
	v_mul_f32_e32 v30, v28, v30
	v_fma_f32 v30, v28, v30, v28
	v_mul_f32_e32 v30, 0x3f4c422a, v30
	v_mul_f32_e32 v30, 0x4038aa3b, v30
	v_exp_f32_e32 v30, v30
	v_mul_f32_e32 v28, 0.5, v28
	v_add_f32_e32 v30, 1.0, v30
	v_rcp_f32_e32 v30, v30
	s_nop 0
	v_fma_f32 v30, v30, -2.0, 1.0
	v_add_f32_e32 v30, 1.0, v30
	v_mul_f32_e32 v28, v28, v30
	v_mul_f32_e32 v30, 0x3d372713, v26
	v_mul_f32_e32 v30, v26, v30
	v_fma_f32 v30, v26, v30, v26
	v_mul_f32_e32 v30, 0x3f4c422a, v30
	v_mul_f32_e32 v30, 0x4038aa3b, v30
	v_exp_f32_e32 v30, v30
	v_mul_f32_e32 v26, 0.5, v26
	v_add_f32_e32 v30, 1.0, v30
	v_rcp_f32_e32 v30, v30
	s_nop 0
	v_fma_f32 v30, v30, -2.0, 1.0
	v_add_f32_e32 v30, 1.0, v30
	v_mul_f32_e32 v40, v26, v30
	v_mul_f32_e32 v26, 0x3d372713, v29
	v_mul_f32_e32 v26, v29, v26
	v_fma_f32 v26, v29, v26, v29
	v_mul_f32_e32 v26, 0x3f4c422a, v26
	v_mul_f32_e32 v26, 0x4038aa3b, v26
	v_exp_f32_e32 v26, v26
	v_mul_f32_e32 v29, 0.5, v29
	v_lshl_add_u64 v[30:31], v[34:35], 0, v[140:141]
	v_lshlrev_b64 v[30:31], 10, v[30:31]
	v_add_f32_e32 v26, 1.0, v26
	v_rcp_f32_e32 v26, v26
	v_lshl_add_u64 v[30:31], s[16:17], 0, v[30:31]
	v_lshl_add_u64 v[30:31], v[30:31], 0, s[46:47]
	v_lshl_add_u64 v[30:31], v[30:31], 0, v[138:139]
	v_fma_f32 v26, v26, -2.0, 1.0
	v_add_f32_e32 v26, 1.0, v26
	v_mul_f32_e32 v29, v29, v26
	v_mul_f32_e32 v26, 0x3d372713, v27
	v_mul_f32_e32 v26, v27, v26
	v_fma_f32 v26, v27, v26, v27
	v_mul_f32_e32 v26, 0x3f4c422a, v26
	v_mul_f32_e32 v26, 0x4038aa3b, v26
	v_exp_f32_e32 v26, v26
	v_mul_f32_e32 v27, 0.5, v27
	v_add_f32_e32 v26, 1.0, v26
	v_rcp_f32_e32 v26, v26
	s_nop 0
	v_fma_f32 v26, v26, -2.0, 1.0
	v_add_f32_e32 v26, 1.0, v26
	v_mul_f32_e32 v41, v27, v26
	v_cvt_pk_bf16_f32 v26, v32, v38
	v_cvt_pk_bf16_f32 v27, v28, v29
	v_cvt_pk_bf16_f32 v28, v33, v39
	v_cvt_pk_bf16_f32 v29, v40, v41
	global_store_dwordx4 v[30:31], v[26:29], off
	s_nop 1
	v_lshl_add_u64 v[26:27], v[36:37], 0, v[122:123]
	v_lshlrev_b64 v[30:31], 5, v[26:27]
	v_or_b32_e32 v30, v30, v138
	v_lshl_add_u64 v[26:27], s[12:13], 0, v[30:31]
	global_load_dwordx4 v[198:201], v143, s[44:45] offset:16
	s_waitcnt vmcnt(5)
	v_lshlrev_b32_e32 v32, 16, v182
	v_and_b32_e32 v33, 0xffff0000, v182
	v_lshlrev_b32_e32 v26, 16, v183
	v_and_b32_e32 v27, 0xffff0000, v183
	v_pk_add_f32 v[32:33], v[18:19], v[32:33]
	v_lshl_add_u64 v[18:19], s[14:15], 0, v[30:31]
	v_lshlrev_b32_e32 v36, 16, v184
	v_and_b32_e32 v37, 0xffff0000, v184
	v_lshlrev_b32_e32 v28, 16, v185
	v_and_b32_e32 v29, 0xffff0000, v185
	v_pk_add_f32 v[38:39], v[20:21], v[26:27]
	global_load_dwordx4 v[170:173], v143, s[44:45]
	s_waitcnt vmcnt(5)
	v_pk_add_f32 v[36:37], v[22:23], v[36:37]
	v_pk_add_f32 v[40:41], v[24:25], v[28:29]
	global_load_dwordx4 v[174:177], v232, s[78:79]
	s_waitcnt vmcnt(5)
	global_load_dwordx4 v[178:181], v233, s[78:79]
	s_waitcnt vmcnt(5)
	v_lshlrev_b32_e32 v30, 16, v186
	v_and_b32_e32 v31, 0xffff0000, v186
	v_lshlrev_b32_e32 v42, 16, v188
	v_and_b32_e32 v43, 0xffff0000, v188
	v_lshlrev_b32_e32 v20, 16, v189
	v_and_b32_e32 v21, 0xffff0000, v189
	v_pk_fma_f32 v[26:27], v[194:195], v[30:31], v[32:33]
	v_pk_fma_f32 v[20:21], v[192:193], v[20:21], v[40:41]
	v_mul_f32_e32 v24, 0x3d372713, v26
	v_mul_f32_e32 v24, v26, v24
	v_fma_f32 v24, v26, v24, v26
	v_mul_f32_e32 v24, 0x3f4c422a, v24
	v_mul_f32_e32 v24, 0x4038aa3b, v24
	v_exp_f32_e32 v24, v24
	v_pk_fma_f32 v[22:23], v[190:191], v[42:43], v[36:37]
	v_mul_f32_e32 v25, 0.5, v26
	v_mul_f32_e32 v26, 0.5, v27
	v_add_f32_e32 v24, 1.0, v24
	v_rcp_f32_e32 v24, v24
	v_lshlrev_b32_e32 v18, 16, v187
	v_and_b32_e32 v19, 0xffff0000, v187
	v_pk_fma_f32 v[18:19], v[196:197], v[18:19], v[38:39]
	v_fma_f32 v24, v24, -2.0, 1.0
	v_add_f32_e32 v24, 1.0, v24
	v_mul_f32_e32 v24, v25, v24
	v_mul_f32_e32 v25, 0x3d372713, v22
	v_mul_f32_e32 v25, v22, v25
	v_fma_f32 v25, v22, v25, v22
	v_mul_f32_e32 v25, 0x3f4c422a, v25
	v_mul_f32_e32 v25, 0x4038aa3b, v25
	v_exp_f32_e32 v25, v25
	v_mul_f32_e32 v22, 0.5, v22
	v_add_f32_e32 v25, 1.0, v25
	v_rcp_f32_e32 v25, v25
	s_nop 0
	v_fma_f32 v25, v25, -2.0, 1.0
	v_add_f32_e32 v25, 1.0, v25
	v_mul_f32_e32 v25, v22, v25
	v_mul_f32_e32 v22, 0x3d372713, v27
	v_mul_f32_e32 v22, v27, v22
	v_fma_f32 v22, v27, v22, v27
	v_mul_f32_e32 v22, 0x3f4c422a, v22
	v_mul_f32_e32 v22, 0x4038aa3b, v22
	v_exp_f32_e32 v22, v22
	s_nop 0
	v_add_f32_e32 v22, 1.0, v22
	v_rcp_f32_e32 v22, v22
	s_nop 0
	v_fma_f32 v22, v22, -2.0, 1.0
	v_add_f32_e32 v22, 1.0, v22
	v_mul_f32_e32 v26, v26, v22
	v_mul_f32_e32 v22, 0x3d372713, v23
	v_mul_f32_e32 v22, v23, v22
	v_fma_f32 v22, v23, v22, v23
	v_mul_f32_e32 v22, 0x3f4c422a, v22
	v_mul_f32_e32 v22, 0x4038aa3b, v22
	v_exp_f32_e32 v22, v22
	v_mul_f32_e32 v23, 0.5, v23
	v_add_f32_e32 v22, 1.0, v22
	v_rcp_f32_e32 v22, v22
	s_nop 0
	v_fma_f32 v22, v22, -2.0, 1.0
	v_add_f32_e32 v22, 1.0, v22
	v_mul_f32_e32 v27, v23, v22
	v_mul_f32_e32 v22, 0x3d372713, v18
	v_mul_f32_e32 v22, v18, v22
	v_fma_f32 v22, v18, v22, v18
	v_mul_f32_e32 v22, 0x3f4c422a, v22
	v_mul_f32_e32 v22, 0x4038aa3b, v22
	v_exp_f32_e32 v22, v22
	v_mul_f32_e32 v18, 0.5, v18
	v_add_f32_e32 v22, 1.0, v22
	v_rcp_f32_e32 v22, v22
	s_nop 0
	v_fma_f32 v22, v22, -2.0, 1.0
	v_add_f32_e32 v22, 1.0, v22
	v_mul_f32_e32 v28, v18, v22
	v_mul_f32_e32 v18, 0x3d372713, v20
	v_mul_f32_e32 v18, v20, v18
	v_fma_f32 v18, v20, v18, v20
	v_mul_f32_e32 v18, 0x3f4c422a, v18
	v_mul_f32_e32 v18, 0x4038aa3b, v18
	v_exp_f32_e32 v18, v18
	v_mul_f32_e32 v20, 0.5, v20
	v_lshl_add_u64 v[22:23], v[34:35], 0, v[122:123]
	v_lshlrev_b64 v[22:23], 10, v[22:23]
	v_add_f32_e32 v18, 1.0, v18
	v_rcp_f32_e32 v18, v18
	v_lshl_add_u64 v[22:23], s[16:17], 0, v[22:23]
	v_lshl_add_u64 v[22:23], v[22:23], 0, s[46:47]
	v_lshl_add_u64 v[22:23], v[22:23], 0, v[138:139]
	v_fma_f32 v18, v18, -2.0, 1.0
	v_add_f32_e32 v18, 1.0, v18
	v_mul_f32_e32 v29, v20, v18
	v_mul_f32_e32 v18, 0x3d372713, v19
	v_mul_f32_e32 v18, v19, v18
	v_fma_f32 v18, v19, v18, v19
	v_mul_f32_e32 v18, 0x3f4c422a, v18
	v_mul_f32_e32 v18, 0x4038aa3b, v18
	v_exp_f32_e32 v18, v18
	v_mul_f32_e32 v19, 0.5, v19
	v_mul_f32_e32 v20, 0.5, v21
	v_add_f32_e32 v18, 1.0, v18
	v_rcp_f32_e32 v18, v18
	s_nop 0
	v_fma_f32 v18, v18, -2.0, 1.0
	v_add_f32_e32 v18, 1.0, v18
	v_mul_f32_e32 v19, v19, v18
	v_mul_f32_e32 v18, 0x3d372713, v21
	v_mul_f32_e32 v18, v21, v18
	v_fma_f32 v18, v21, v18, v21
	v_mul_f32_e32 v18, 0x3f4c422a, v18
	v_mul_f32_e32 v18, 0x4038aa3b, v18
	v_exp_f32_e32 v18, v18
	v_cvt_pk_bf16_f32 v19, v28, v19
	v_add_f32_e32 v18, 1.0, v18
	v_rcp_f32_e32 v18, v18
	s_nop 0
	v_fma_f32 v18, v18, -2.0, 1.0
	v_add_f32_e32 v18, 1.0, v18
	v_mul_f32_e32 v21, v20, v18
	v_cvt_pk_bf16_f32 v18, v24, v26
	v_cvt_pk_bf16_f32 v20, v25, v27
	v_cvt_pk_bf16_f32 v21, v29, v21
	global_store_dwordx4 v[22:23], v[18:21], off
	global_load_dwordx4 v[182:185], v240, s[78:79]
	s_waitcnt vmcnt(5)
	s_nop 0
	global_load_dwordx4 v[186:189], v241, s[78:79]
	s_waitcnt vmcnt(5)
	v_add_u32_e32 v18, 0xb0, v142
	v_ashrrev_i32_e32 v19, 31, v18
	v_lshlrev_b64 v[18:19], 5, v[18:19]
	v_lshl_add_u64 v[20:21], v[18:19], 0, s[60:61]
	v_lshl_add_u64 v[30:31], v[20:21], 0, v[140:141]
	v_lshlrev_b64 v[34:35], 5, v[30:31]
	v_or_b32_e32 v34, v34, v138
	v_lshl_add_u64 v[30:31], s[12:13], 0, v[34:35]
	global_load_dwordx4 v[190:193], v143, s[44:45] offset:16
	s_waitcnt vmcnt(5)
	v_lshlrev_b32_e32 v36, 16, v174
	v_and_b32_e32 v37, 0xffff0000, v174
	v_lshlrev_b32_e32 v30, 16, v175
	v_and_b32_e32 v31, 0xffff0000, v175
	v_pk_add_f32 v[36:37], v[10:11], v[36:37]
	v_lshl_add_u64 v[10:11], s[14:15], 0, v[34:35]
	v_pk_add_f32 v[30:31], v[12:13], v[30:31]
	global_load_dwordx4 v[194:197], v143, s[44:45]
	s_waitcnt vmcnt(5)
	v_lshlrev_b32_e32 v38, 16, v176
	v_and_b32_e32 v39, 0xffff0000, v176
	v_lshlrev_b32_e32 v32, 16, v177
	v_and_b32_e32 v33, 0xffff0000, v177
	v_pk_add_f32 v[16:17], v[16:17], v[32:33]
	v_pk_add_f32 v[14:15], v[14:15], v[38:39]
	v_lshlrev_b32_e32 v32, 16, v178
	v_and_b32_e32 v33, 0xffff0000, v178
	v_lshlrev_b32_e32 v10, 16, v179
	v_and_b32_e32 v11, 0xffff0000, v179
	v_lshlrev_b32_e32 v38, 16, v181
	v_and_b32_e32 v39, 0xffff0000, v181
	v_pk_fma_f32 v[26:27], v[170:171], v[32:33], v[36:37]
	v_lshlrev_b32_e32 v34, 16, v180
	v_and_b32_e32 v35, 0xffff0000, v180
	v_pk_fma_f32 v[12:13], v[172:173], v[10:11], v[30:31]
	v_pk_fma_f32 v[10:11], v[200:201], v[38:39], v[16:17]
	v_mul_f32_e32 v16, 0x3d372713, v26
	v_mul_f32_e32 v16, v26, v16
	v_fma_f32 v16, v26, v16, v26
	v_mul_f32_e32 v16, 0x3f4c422a, v16
	v_mul_f32_e32 v16, 0x4038aa3b, v16
	v_exp_f32_e32 v16, v16
	v_pk_fma_f32 v[14:15], v[198:199], v[34:35], v[14:15]
	v_mul_f32_e32 v17, 0.5, v26
	v_mul_f32_e32 v22, 0.5, v27
	v_add_f32_e32 v16, 1.0, v16
	v_rcp_f32_e32 v16, v16
	s_nop 0
	v_fma_f32 v16, v16, -2.0, 1.0
	v_add_f32_e32 v16, 1.0, v16
	v_mul_f32_e32 v16, v17, v16
	v_mul_f32_e32 v17, 0x3d372713, v14
	v_mul_f32_e32 v17, v14, v17
	v_fma_f32 v17, v14, v17, v14
	v_mul_f32_e32 v17, 0x3f4c422a, v17
	v_mul_f32_e32 v17, 0x4038aa3b, v17
	v_exp_f32_e32 v17, v17
	v_mul_f32_e32 v14, 0.5, v14
	v_add_f32_e32 v17, 1.0, v17
	v_rcp_f32_e32 v17, v17
	s_nop 0
	v_fma_f32 v17, v17, -2.0, 1.0
	v_add_f32_e32 v17, 1.0, v17
	v_mul_f32_e32 v17, v14, v17
	v_mul_f32_e32 v14, 0x3d372713, v27
	v_mul_f32_e32 v14, v27, v14
	v_fma_f32 v14, v27, v14, v27
	v_mul_f32_e32 v14, 0x3f4c422a, v14
	v_mul_f32_e32 v14, 0x4038aa3b, v14
	v_exp_f32_e32 v14, v14
	s_nop 0
	v_add_f32_e32 v14, 1.0, v14
	v_rcp_f32_e32 v14, v14
	s_nop 0
	v_fma_f32 v14, v14, -2.0, 1.0
	v_add_f32_e32 v14, 1.0, v14
	v_mul_f32_e32 v22, v22, v14
	v_mul_f32_e32 v14, 0x3d372713, v15
	v_mul_f32_e32 v14, v15, v14
	v_fma_f32 v14, v15, v14, v15
	v_mul_f32_e32 v14, 0x3f4c422a, v14
	v_mul_f32_e32 v14, 0x4038aa3b, v14
	v_exp_f32_e32 v14, v14
	v_mul_f32_e32 v15, 0.5, v15
	v_add_f32_e32 v14, 1.0, v14
	v_rcp_f32_e32 v14, v14
	s_nop 0
	v_fma_f32 v14, v14, -2.0, 1.0
	v_add_f32_e32 v14, 1.0, v14
	v_mul_f32_e32 v23, v15, v14
	v_mul_f32_e32 v14, 0x3d372713, v12
	v_mul_f32_e32 v14, v12, v14
	v_fma_f32 v14, v12, v14, v12
	v_mul_f32_e32 v14, 0x3f4c422a, v14
	v_mul_f32_e32 v14, 0x4038aa3b, v14
	v_exp_f32_e32 v14, v14
	v_mul_f32_e32 v12, 0.5, v12
	v_add_f32_e32 v14, 1.0, v14
	v_rcp_f32_e32 v14, v14
	s_nop 0
	v_fma_f32 v14, v14, -2.0, 1.0
	v_add_f32_e32 v14, 1.0, v14
	v_mul_f32_e32 v12, v12, v14
	v_mul_f32_e32 v14, 0x3d372713, v10
	v_mul_f32_e32 v14, v10, v14
	v_fma_f32 v14, v10, v14, v10
	v_mul_f32_e32 v14, 0x3f4c422a, v14
	v_mul_f32_e32 v14, 0x4038aa3b, v14
	v_exp_f32_e32 v14, v14
	v_mul_f32_e32 v10, 0.5, v10
	v_add_f32_e32 v14, 1.0, v14
	v_rcp_f32_e32 v14, v14
	s_nop 0
	v_fma_f32 v14, v14, -2.0, 1.0
	v_add_f32_e32 v14, 1.0, v14
	v_mul_f32_e32 v24, v10, v14
	v_mul_f32_e32 v10, 0x3d372713, v13
	v_mul_f32_e32 v10, v13, v10
	v_fma_f32 v10, v13, v10, v13
	v_mul_f32_e32 v10, 0x3f4c422a, v10
	v_mul_f32_e32 v10, 0x4038aa3b, v10
	v_exp_f32_e32 v10, v10
	v_mul_f32_e32 v13, 0.5, v13
	v_lshl_add_u64 v[14:15], v[18:19], 0, v[140:141]
	v_lshlrev_b64 v[14:15], 10, v[14:15]
	v_add_f32_e32 v10, 1.0, v10
	v_rcp_f32_e32 v10, v10
	v_lshl_add_u64 v[14:15], s[16:17], 0, v[14:15]
	v_lshl_add_u64 v[14:15], v[14:15], 0, s[46:47]
	v_lshl_add_u64 v[14:15], v[14:15], 0, v[138:139]
	v_fma_f32 v10, v10, -2.0, 1.0
	v_add_f32_e32 v10, 1.0, v10
	v_mul_f32_e32 v13, v13, v10
	v_mul_f32_e32 v10, 0x3d372713, v11
	v_mul_f32_e32 v10, v11, v10
	v_fma_f32 v10, v11, v10, v11
	v_mul_f32_e32 v10, 0x3f4c422a, v10
	v_mul_f32_e32 v10, 0x4038aa3b, v10
	v_exp_f32_e32 v10, v10
	v_mul_f32_e32 v11, 0.5, v11
	v_add_f32_e32 v10, 1.0, v10
	v_rcp_f32_e32 v10, v10
	s_nop 0
	v_fma_f32 v10, v10, -2.0, 1.0
	v_add_f32_e32 v10, 1.0, v10
	v_mul_f32_e32 v25, v11, v10
	v_cvt_pk_bf16_f32 v10, v16, v22
	v_cvt_pk_bf16_f32 v11, v12, v13
	v_cvt_pk_bf16_f32 v12, v17, v23
	v_cvt_pk_bf16_f32 v13, v24, v25
	global_store_dwordx4 v[14:15], v[10:13], off
	s_nop 1
	v_lshl_add_u64 v[10:11], v[20:21], 0, v[122:123]
	v_lshlrev_b64 v[14:15], 5, v[10:11]
	v_or_b32_e32 v14, v14, v138
	v_lshl_add_u64 v[10:11], s[12:13], 0, v[14:15]
	s_waitcnt vmcnt(4)
	v_lshlrev_b32_e32 v16, 16, v182
	v_and_b32_e32 v17, 0xffff0000, v182
	v_lshlrev_b32_e32 v10, 16, v183
	v_and_b32_e32 v11, 0xffff0000, v183
	v_pk_add_f32 v[16:17], v[2:3], v[16:17]
	v_lshl_add_u64 v[2:3], s[14:15], 0, v[14:15]
	v_lshlrev_b32_e32 v20, 16, v184
	v_and_b32_e32 v21, 0xffff0000, v184
	v_lshlrev_b32_e32 v12, 16, v185
	v_and_b32_e32 v13, 0xffff0000, v185
	v_pk_add_f32 v[22:23], v[4:5], v[10:11]
	s_waitcnt vmcnt(3)
	v_pk_add_f32 v[20:21], v[6:7], v[20:21]
	v_pk_add_f32 v[24:25], v[8:9], v[12:13]
	s_waitcnt vmcnt(2)
	s_waitcnt vmcnt(1)
	s_mov_b64 s[44:45], -1
	v_lshlrev_b32_e32 v14, 16, v186
	v_and_b32_e32 v15, 0xffff0000, v186
	v_lshlrev_b32_e32 v26, 16, v188
	v_and_b32_e32 v27, 0xffff0000, v188
	v_lshlrev_b32_e32 v4, 16, v189
	v_and_b32_e32 v5, 0xffff0000, v189
	v_pk_fma_f32 v[10:11], v[194:195], v[14:15], v[16:17]
	v_pk_fma_f32 v[4:5], v[192:193], v[4:5], v[24:25]
	v_mul_f32_e32 v8, 0x3d372713, v10
	v_mul_f32_e32 v8, v10, v8
	v_fma_f32 v8, v10, v8, v10
	v_mul_f32_e32 v8, 0x3f4c422a, v8
	v_mul_f32_e32 v8, 0x4038aa3b, v8
	v_exp_f32_e32 v8, v8
	v_pk_fma_f32 v[6:7], v[190:191], v[26:27], v[20:21]
	v_mul_f32_e32 v9, 0.5, v10
	v_mul_f32_e32 v10, 0.5, v11
	v_add_f32_e32 v8, 1.0, v8
	v_rcp_f32_e32 v8, v8
	v_lshlrev_b32_e32 v2, 16, v187
	v_and_b32_e32 v3, 0xffff0000, v187
	v_pk_fma_f32 v[2:3], v[196:197], v[2:3], v[22:23]
	v_fma_f32 v8, v8, -2.0, 1.0
	v_add_f32_e32 v8, 1.0, v8
	v_mul_f32_e32 v8, v9, v8
	v_mul_f32_e32 v9, 0x3d372713, v6
	v_mul_f32_e32 v9, v6, v9
	v_fma_f32 v9, v6, v9, v6
	v_mul_f32_e32 v9, 0x3f4c422a, v9
	v_mul_f32_e32 v9, 0x4038aa3b, v9
	v_exp_f32_e32 v9, v9
	v_mul_f32_e32 v6, 0.5, v6
	v_add_f32_e32 v9, 1.0, v9
	v_rcp_f32_e32 v9, v9
	s_nop 0
	v_fma_f32 v9, v9, -2.0, 1.0
	v_add_f32_e32 v9, 1.0, v9
	v_mul_f32_e32 v9, v6, v9
	v_mul_f32_e32 v6, 0x3d372713, v11
	v_mul_f32_e32 v6, v11, v6
	v_fma_f32 v6, v11, v6, v11
	v_mul_f32_e32 v6, 0x3f4c422a, v6
	v_mul_f32_e32 v6, 0x4038aa3b, v6
	v_exp_f32_e32 v6, v6
	s_nop 0
	v_add_f32_e32 v6, 1.0, v6
	v_rcp_f32_e32 v6, v6
	s_nop 0
	v_fma_f32 v6, v6, -2.0, 1.0
	v_add_f32_e32 v6, 1.0, v6
	v_mul_f32_e32 v10, v10, v6
	v_mul_f32_e32 v6, 0x3d372713, v7
	v_mul_f32_e32 v6, v7, v6
	v_fma_f32 v6, v7, v6, v7
	v_mul_f32_e32 v6, 0x3f4c422a, v6
	v_mul_f32_e32 v6, 0x4038aa3b, v6
	v_exp_f32_e32 v6, v6
	v_mul_f32_e32 v7, 0.5, v7
	v_add_f32_e32 v6, 1.0, v6
	v_rcp_f32_e32 v6, v6
	s_nop 0
	v_fma_f32 v6, v6, -2.0, 1.0
	v_add_f32_e32 v6, 1.0, v6
	v_mul_f32_e32 v11, v7, v6
	v_mul_f32_e32 v6, 0x3d372713, v2
	v_mul_f32_e32 v6, v2, v6
	v_fma_f32 v6, v2, v6, v2
	v_mul_f32_e32 v6, 0x3f4c422a, v6
	v_mul_f32_e32 v6, 0x4038aa3b, v6
	v_exp_f32_e32 v6, v6
	v_mul_f32_e32 v2, 0.5, v2
	v_add_f32_e32 v6, 1.0, v6
	v_rcp_f32_e32 v6, v6
	s_nop 0
	v_fma_f32 v6, v6, -2.0, 1.0
	v_add_f32_e32 v6, 1.0, v6
	v_mul_f32_e32 v12, v2, v6
	v_mul_f32_e32 v2, 0x3d372713, v4
	v_mul_f32_e32 v2, v4, v2
	v_fma_f32 v2, v4, v2, v4
	v_mul_f32_e32 v2, 0x3f4c422a, v2
	v_mul_f32_e32 v2, 0x4038aa3b, v2
	v_exp_f32_e32 v2, v2
	v_mul_f32_e32 v4, 0.5, v4
	v_lshl_add_u64 v[6:7], v[18:19], 0, v[122:123]
	v_lshlrev_b64 v[6:7], 10, v[6:7]
	v_add_f32_e32 v2, 1.0, v2
	v_rcp_f32_e32 v2, v2
	v_lshl_add_u64 v[6:7], s[16:17], 0, v[6:7]
	v_lshl_add_u64 v[6:7], v[6:7], 0, s[46:47]
	v_lshl_add_u64 v[6:7], v[6:7], 0, v[138:139]
	v_fma_f32 v2, v2, -2.0, 1.0
	v_add_f32_e32 v2, 1.0, v2
	v_mul_f32_e32 v13, v4, v2
	v_mul_f32_e32 v2, 0x3d372713, v3
	v_mul_f32_e32 v2, v3, v2
	v_fma_f32 v2, v3, v2, v3
	v_mul_f32_e32 v2, 0x3f4c422a, v2
	v_mul_f32_e32 v2, 0x4038aa3b, v2
	v_exp_f32_e32 v2, v2
	v_mul_f32_e32 v3, 0.5, v3
	v_mul_f32_e32 v4, 0.5, v5
	v_add_f32_e32 v2, 1.0, v2
	v_rcp_f32_e32 v2, v2
	s_nop 0
	v_fma_f32 v2, v2, -2.0, 1.0
	v_add_f32_e32 v2, 1.0, v2
	v_mul_f32_e32 v3, v3, v2
	v_mul_f32_e32 v2, 0x3d372713, v5
	v_mul_f32_e32 v2, v5, v2
	v_fma_f32 v2, v5, v2, v5
	v_mul_f32_e32 v2, 0x3f4c422a, v2
	v_mul_f32_e32 v2, 0x4038aa3b, v2
	v_exp_f32_e32 v2, v2
	v_cvt_pk_bf16_f32 v3, v12, v3
	v_add_f32_e32 v2, 1.0, v2
	v_rcp_f32_e32 v2, v2
	s_nop 0
	v_fma_f32 v2, v2, -2.0, 1.0
	v_add_f32_e32 v2, 1.0, v2
	v_mul_f32_e32 v5, v4, v2
	v_cvt_pk_bf16_f32 v2, v8, v10
	v_cvt_pk_bf16_f32 v4, v9, v11
	v_cvt_pk_bf16_f32 v5, v13, v5
	global_store_dwordx4 v[6:7], v[2:5], off
	s_cbranch_vccnz .LBB0_402
	s_andn2_b64 vcc, exec, s[10:11]
	s_cbranch_vccnz .LBB0_401
	s_barrier
	s_branch .LBB0_401
